# FFN-up loop: barrier moved to mid-step so the 3-stage ring keeps two LDS-DMA tiles in flight with fragments still prefetched half a step ahead
# speedup vs baseline: 1.0175x; 1.0175x over previous
.Lhw_ffnup_dloop:
	s_cmp_ge_u32 s2, s64
	s_cbranch_scc1 .Lhw_ffnup_tail
	s_mul_i32 s6, s2, 745
	s_lshr_b32 s6, s6, 16
	s_mul_i32 s14, s6, 88
	s_sub_i32 s14, s2, s14
	v_readlane_b32 s13, v246, 16
	s_lshl_b32 s6, s6, 2
	s_and_b32 s12, s14, 3
	s_add_i32 s6, s6, s12
	s_add_i32 s6, s6, s13
	s_lshl_b32 s6, s6, 7
	s_lshr_b32 s14, s14, 2
	s_lshl_b32 s14, s14, 8
	s_lshl_b32 vcc_lo, s6, 11
	s_add_u32 s66, s10, vcc_lo
	s_addc_u32 s67, s11, 0
	s_lshl_b32 vcc_lo, s14, 11
	s_add_u32 s12, s0, vcc_lo
	s_addc_u32 s13, s1, 0
	s_add_u32 s62, s12, 0x40000
	s_addc_u32 s63, s13, 0
	s_barrier
	s_add_u32 m0, s65, 0x0
	s_nop 0
	global_load_lds_dwordx4 v160, s[66:67]
	s_add_u32 m0, s65, 0x1000
	s_nop 0
	global_load_lds_dwordx4 v161, s[66:67]
	s_add_u32 m0, s65, 0x2000
	s_nop 0
	global_load_lds_dwordx4 v160, s[12:13]
	s_add_u32 m0, s65, 0x3000
	s_nop 0
	global_load_lds_dwordx4 v161, s[12:13]
	s_add_u32 m0, s65, 0x4000
	s_nop 0
	global_load_lds_dwordx4 v160, s[62:63]
	s_add_u32 m0, s65, 0x5000
	s_nop 0
	global_load_lds_dwordx4 v161, s[62:63]
	s_add_u32 s66, s66, 64
	s_addc_u32 s67, s67, 0
	s_add_u32 s12, s12, 64
	s_addc_u32 s13, s13, 0
	s_add_u32 s62, s62, 64
	s_addc_u32 s63, s63, 0
	s_add_u32 m0, s65, 0x6000
	s_nop 0
	global_load_lds_dwordx4 v160, s[66:67]
	s_add_u32 m0, s65, 0x7000
	s_nop 0
	global_load_lds_dwordx4 v161, s[66:67]
	s_add_u32 m0, s65, 0x8000
	s_nop 0
	global_load_lds_dwordx4 v160, s[12:13]
	s_add_u32 m0, s65, 0x9000
	s_nop 0
	global_load_lds_dwordx4 v161, s[12:13]
	s_add_u32 m0, s65, 0xa000
	s_nop 0
	global_load_lds_dwordx4 v160, s[62:63]
	s_add_u32 m0, s65, 0xb000
	s_nop 0
	global_load_lds_dwordx4 v161, s[62:63]
	s_add_u32 s66, s66, 64
	s_addc_u32 s67, s67, 0
	s_add_u32 s12, s12, 64
	s_addc_u32 s13, s13, 0
	s_add_u32 s62, s62, 64
	s_addc_u32 s63, s63, 0
	s_add_u32 m0, s65, 0xc000
	s_nop 0
	global_load_lds_dwordx4 v160, s[66:67]
	s_add_u32 m0, s65, 0xd000
	s_nop 0
	global_load_lds_dwordx4 v161, s[66:67]
	s_add_u32 m0, s65, 0xe000
	s_nop 0
	global_load_lds_dwordx4 v160, s[12:13]
	s_add_u32 m0, s65, 0xf000
	s_nop 0
	global_load_lds_dwordx4 v161, s[12:13]
	s_add_u32 m0, s65, 0x10000
	s_nop 0
	global_load_lds_dwordx4 v160, s[62:63]
	s_add_u32 m0, s65, 0x11000
	s_nop 0
	global_load_lds_dwordx4 v161, s[62:63]
	s_add_u32 s66, s66, 64
	s_addc_u32 s67, s67, 0
	s_add_u32 s12, s12, 64
	s_addc_u32 s13, s13, 0
	s_add_u32 s62, s62, 64
	s_addc_u32 s63, s63, 0
	v_mov_b32_e32 v2, 0
	v_mov_b32_e32 v3, 0
	v_mov_b32_e32 v4, 0
	v_mov_b32_e32 v5, 0
	v_mov_b32_e32 v6, 0
	v_mov_b32_e32 v7, 0
	v_mov_b32_e32 v8, 0
	v_mov_b32_e32 v9, 0
	v_mov_b32_e32 v10, 0
	v_mov_b32_e32 v11, 0
	v_mov_b32_e32 v12, 0
	v_mov_b32_e32 v13, 0
	v_mov_b32_e32 v14, 0
	v_mov_b32_e32 v15, 0
	v_mov_b32_e32 v16, 0
	v_mov_b32_e32 v17, 0
	v_mov_b32_e32 v18, 0
	v_mov_b32_e32 v19, 0
	v_mov_b32_e32 v20, 0
	v_mov_b32_e32 v21, 0
	v_mov_b32_e32 v22, 0
	v_mov_b32_e32 v23, 0
	v_mov_b32_e32 v24, 0
	v_mov_b32_e32 v25, 0
	v_mov_b32_e32 v26, 0
	v_mov_b32_e32 v27, 0
	v_mov_b32_e32 v28, 0
	v_mov_b32_e32 v29, 0
	v_mov_b32_e32 v30, 0
	v_mov_b32_e32 v31, 0
	v_mov_b32_e32 v32, 0
	v_mov_b32_e32 v33, 0
	v_mov_b32_e32 v34, 0
	v_mov_b32_e32 v35, 0
	v_mov_b32_e32 v36, 0
	v_mov_b32_e32 v37, 0
	v_mov_b32_e32 v38, 0
	v_mov_b32_e32 v39, 0
	v_mov_b32_e32 v40, 0
	v_mov_b32_e32 v41, 0
	v_mov_b32_e32 v42, 0
	v_mov_b32_e32 v43, 0
	v_mov_b32_e32 v44, 0
	v_mov_b32_e32 v45, 0
	v_mov_b32_e32 v46, 0
	v_mov_b32_e32 v47, 0
	v_mov_b32_e32 v48, 0
	v_mov_b32_e32 v49, 0
	v_mov_b32_e32 v50, 0
	v_mov_b32_e32 v51, 0
	v_mov_b32_e32 v52, 0
	v_mov_b32_e32 v53, 0
	v_mov_b32_e32 v54, 0
	v_mov_b32_e32 v55, 0
	v_mov_b32_e32 v56, 0
	v_mov_b32_e32 v57, 0
	v_mov_b32_e32 v58, 0
	v_mov_b32_e32 v59, 0
	v_mov_b32_e32 v60, 0
	v_mov_b32_e32 v61, 0
	v_mov_b32_e32 v62, 0
	v_mov_b32_e32 v63, 0
	v_mov_b32_e32 v64, 0
	v_mov_b32_e32 v65, 0
	v_mov_b32_e32 v66, 0
	v_mov_b32_e32 v67, 0
	v_mov_b32_e32 v68, 0
	v_mov_b32_e32 v69, 0
	v_mov_b32_e32 v70, 0
	v_mov_b32_e32 v71, 0
	v_mov_b32_e32 v72, 0
	v_mov_b32_e32 v73, 0
	v_mov_b32_e32 v74, 0
	v_mov_b32_e32 v75, 0
	v_mov_b32_e32 v76, 0
	v_mov_b32_e32 v77, 0
	v_mov_b32_e32 v78, 0
	v_mov_b32_e32 v79, 0
	v_mov_b32_e32 v80, 0
	v_mov_b32_e32 v81, 0
	v_mov_b32_e32 v82, 0
	v_mov_b32_e32 v83, 0
	v_mov_b32_e32 v84, 0
	v_mov_b32_e32 v85, 0
	v_mov_b32_e32 v86, 0
	v_mov_b32_e32 v87, 0
	v_mov_b32_e32 v88, 0
	v_mov_b32_e32 v89, 0
	v_mov_b32_e32 v90, 0
	v_mov_b32_e32 v91, 0
	v_mov_b32_e32 v92, 0
	v_mov_b32_e32 v93, 0
	v_mov_b32_e32 v94, 0
	v_mov_b32_e32 v95, 0
	v_mov_b32_e32 v96, 0
	v_mov_b32_e32 v97, 0
	v_mov_b32_e32 v98, 0
	v_mov_b32_e32 v99, 0
	v_mov_b32_e32 v100, 0
	v_mov_b32_e32 v101, 0
	v_mov_b32_e32 v102, 0
	v_mov_b32_e32 v103, 0
	v_mov_b32_e32 v104, 0
	v_mov_b32_e32 v105, 0
	v_mov_b32_e32 v106, 0
	v_mov_b32_e32 v107, 0
	v_mov_b32_e32 v108, 0
	v_mov_b32_e32 v109, 0
	v_mov_b32_e32 v110, 0
	v_mov_b32_e32 v111, 0
	v_mov_b32_e32 v112, 0
	v_mov_b32_e32 v113, 0
	v_mov_b32_e32 v114, 0
	v_mov_b32_e32 v115, 0
	v_mov_b32_e32 v116, 0
	v_mov_b32_e32 v117, 0
	v_mov_b32_e32 v118, 0
	v_mov_b32_e32 v119, 0
	v_mov_b32_e32 v120, 0
	v_mov_b32_e32 v121, 0
	v_mov_b32_e32 v122, 0
	v_mov_b32_e32 v123, 0
	v_mov_b32_e32 v124, 0
	v_mov_b32_e32 v125, 0
	v_mov_b32_e32 v126, 0
	v_mov_b32_e32 v127, 0
	v_mov_b32_e32 v128, 0
	v_mov_b32_e32 v129, 0
	s_waitcnt vmcnt(12)
	s_barrier
	ds_read_b128 v[130:133], v154 offset:16
	ds_read_b128 v[138:141], v156 offset:8208
	ds_read_b128 v[142:145], v156 offset:10256
	ds_read_b128 v[134:137], v154 offset:2064
	ds_read_b128 v[146:149], v158 offset:8208
	ds_read_b128 v[150:153], v158 offset:10256
	s_mov_b32 s59, 9
.Lhw_ffnup_d_loop:
	s_waitcnt lgkmcnt(4)
	v_mfma_f32_32x32x16_bf16 v[2:17], v[130:133], v[138:141], v[2:17]
	ds_read_b128 v[212:215], v155 offset:16
	s_waitcnt lgkmcnt(4)
	v_mfma_f32_32x32x16_bf16 v[18:33], v[130:133], v[142:145], v[18:33]
	ds_read_b128 v[220:223], v157 offset:8208
	s_waitcnt lgkmcnt(4)
	v_mfma_f32_32x32x16_bf16 v[34:49], v[134:137], v[138:141], v[34:49]
	ds_read_b128 v[224:227], v157 offset:10256
	s_waitcnt lgkmcnt(5)
	v_mfma_f32_32x32x16_bf16 v[50:65], v[134:137], v[142:145], v[50:65]
	ds_read_b128 v[216:219], v155 offset:2064
	s_waitcnt lgkmcnt(5)
	v_mfma_f32_32x32x16_bf16 v[66:81], v[130:133], v[146:149], v[66:81]
	ds_read_b128 v[228:231], v159 offset:8208
	s_waitcnt lgkmcnt(5)
	v_mfma_f32_32x32x16_bf16 v[82:97], v[130:133], v[150:153], v[82:97]
	ds_read_b128 v[232:235], v159 offset:10256
	s_waitcnt lgkmcnt(7)
	v_mfma_f32_32x32x16_bf16 v[98:113], v[134:137], v[146:149], v[98:113]
	s_waitcnt lgkmcnt(6)
	v_mfma_f32_32x32x16_bf16 v[114:129], v[134:137], v[150:153], v[114:129]
	s_waitcnt vmcnt(6) lgkmcnt(0)
	s_barrier
	v_mfma_f32_32x32x16_bf16 v[2:17], v[212:215], v[220:223], v[2:17]
	s_add_u32 m0, s65, 0x0
	ds_read_b128 v[130:133], v154 offset:24592
	global_load_lds_dwordx4 v160, s[66:67]
	v_mfma_f32_32x32x16_bf16 v[18:33], v[212:215], v[224:227], v[18:33]
	s_add_u32 m0, s65, 0x1000
	ds_read_b128 v[138:141], v156 offset:32784
	global_load_lds_dwordx4 v161, s[66:67]
	v_mfma_f32_32x32x16_bf16 v[34:49], v[216:219], v[220:223], v[34:49]
	s_add_u32 m0, s65, 0x2000
	ds_read_b128 v[142:145], v156 offset:34832
	global_load_lds_dwordx4 v160, s[12:13]
	v_mfma_f32_32x32x16_bf16 v[50:65], v[216:219], v[224:227], v[50:65]
	s_add_u32 m0, s65, 0x3000
	ds_read_b128 v[134:137], v154 offset:26640
	global_load_lds_dwordx4 v161, s[12:13]
	v_mfma_f32_32x32x16_bf16 v[66:81], v[212:215], v[228:231], v[66:81]
	s_add_u32 m0, s65, 0x4000
	ds_read_b128 v[146:149], v158 offset:32784
	global_load_lds_dwordx4 v160, s[62:63]
	v_mfma_f32_32x32x16_bf16 v[82:97], v[212:215], v[232:235], v[82:97]
	s_add_u32 m0, s65, 0x5000
	ds_read_b128 v[150:153], v158 offset:34832
	global_load_lds_dwordx4 v161, s[62:63]
	v_mfma_f32_32x32x16_bf16 v[98:113], v[216:219], v[228:231], v[98:113]
	s_add_u32 s66, s66, 64
	s_addc_u32 s67, s67, 0
	s_add_u32 s12, s12, 64
	s_addc_u32 s13, s13, 0
	v_mfma_f32_32x32x16_bf16 v[114:129], v[216:219], v[232:235], v[114:129]
	s_add_u32 s62, s62, 64
	s_addc_u32 s63, s63, 0
	s_waitcnt lgkmcnt(4)
	v_mfma_f32_32x32x16_bf16 v[2:17], v[130:133], v[138:141], v[2:17]
	ds_read_b128 v[212:215], v155 offset:24592
	s_waitcnt lgkmcnt(4)
	v_mfma_f32_32x32x16_bf16 v[18:33], v[130:133], v[142:145], v[18:33]
	ds_read_b128 v[220:223], v157 offset:32784
	s_waitcnt lgkmcnt(4)
	v_mfma_f32_32x32x16_bf16 v[34:49], v[134:137], v[138:141], v[34:49]
	ds_read_b128 v[224:227], v157 offset:34832
	s_waitcnt lgkmcnt(5)
	v_mfma_f32_32x32x16_bf16 v[50:65], v[134:137], v[142:145], v[50:65]
	ds_read_b128 v[216:219], v155 offset:26640
	s_waitcnt lgkmcnt(5)
	v_mfma_f32_32x32x16_bf16 v[66:81], v[130:133], v[146:149], v[66:81]
	ds_read_b128 v[228:231], v159 offset:32784
	s_waitcnt lgkmcnt(5)
	v_mfma_f32_32x32x16_bf16 v[82:97], v[130:133], v[150:153], v[82:97]
	ds_read_b128 v[232:235], v159 offset:34832
	s_waitcnt lgkmcnt(7)
	v_mfma_f32_32x32x16_bf16 v[98:113], v[134:137], v[146:149], v[98:113]
	s_waitcnt lgkmcnt(6)
	v_mfma_f32_32x32x16_bf16 v[114:129], v[134:137], v[150:153], v[114:129]
	s_waitcnt vmcnt(6) lgkmcnt(0)
	s_barrier
	v_mfma_f32_32x32x16_bf16 v[2:17], v[212:215], v[220:223], v[2:17]
	s_add_u32 m0, s65, 0x6000
	ds_read_b128 v[130:133], v154 offset:49168
	global_load_lds_dwordx4 v160, s[66:67]
	v_mfma_f32_32x32x16_bf16 v[18:33], v[212:215], v[224:227], v[18:33]
	s_add_u32 m0, s65, 0x7000
	ds_read_b128 v[138:141], v156 offset:57360
	global_load_lds_dwordx4 v161, s[66:67]
	v_mfma_f32_32x32x16_bf16 v[34:49], v[216:219], v[220:223], v[34:49]
	s_add_u32 m0, s65, 0x8000
	ds_read_b128 v[142:145], v156 offset:59408
	global_load_lds_dwordx4 v160, s[12:13]
	v_mfma_f32_32x32x16_bf16 v[50:65], v[216:219], v[224:227], v[50:65]
	s_add_u32 m0, s65, 0x9000
	ds_read_b128 v[134:137], v154 offset:51216
	global_load_lds_dwordx4 v161, s[12:13]
	v_mfma_f32_32x32x16_bf16 v[66:81], v[212:215], v[228:231], v[66:81]
	s_add_u32 m0, s65, 0xa000
	ds_read_b128 v[146:149], v158 offset:57360
	global_load_lds_dwordx4 v160, s[62:63]
	v_mfma_f32_32x32x16_bf16 v[82:97], v[212:215], v[232:235], v[82:97]
	s_add_u32 m0, s65, 0xb000
	ds_read_b128 v[150:153], v158 offset:59408
	global_load_lds_dwordx4 v161, s[62:63]
	v_mfma_f32_32x32x16_bf16 v[98:113], v[216:219], v[228:231], v[98:113]
	s_add_u32 s66, s66, 64
	s_addc_u32 s67, s67, 0
	s_add_u32 s12, s12, 64
	s_addc_u32 s13, s13, 0
	v_mfma_f32_32x32x16_bf16 v[114:129], v[216:219], v[232:235], v[114:129]
	s_add_u32 s62, s62, 64
	s_addc_u32 s63, s63, 0
	s_waitcnt lgkmcnt(4)
	v_mfma_f32_32x32x16_bf16 v[2:17], v[130:133], v[138:141], v[2:17]
	ds_read_b128 v[212:215], v155 offset:49168
	s_waitcnt lgkmcnt(4)
	v_mfma_f32_32x32x16_bf16 v[18:33], v[130:133], v[142:145], v[18:33]
	ds_read_b128 v[220:223], v157 offset:57360
	s_waitcnt lgkmcnt(4)
	v_mfma_f32_32x32x16_bf16 v[34:49], v[134:137], v[138:141], v[34:49]
	ds_read_b128 v[224:227], v157 offset:59408
	s_waitcnt lgkmcnt(5)
	v_mfma_f32_32x32x16_bf16 v[50:65], v[134:137], v[142:145], v[50:65]
	ds_read_b128 v[216:219], v155 offset:51216
	s_waitcnt lgkmcnt(5)
	v_mfma_f32_32x32x16_bf16 v[66:81], v[130:133], v[146:149], v[66:81]
	ds_read_b128 v[228:231], v159 offset:57360
	s_waitcnt lgkmcnt(5)
	v_mfma_f32_32x32x16_bf16 v[82:97], v[130:133], v[150:153], v[82:97]
	ds_read_b128 v[232:235], v159 offset:59408
	s_waitcnt lgkmcnt(7)
	v_mfma_f32_32x32x16_bf16 v[98:113], v[134:137], v[146:149], v[98:113]
	s_waitcnt lgkmcnt(6)
	v_mfma_f32_32x32x16_bf16 v[114:129], v[134:137], v[150:153], v[114:129]
	s_waitcnt vmcnt(6) lgkmcnt(0)
	s_barrier
	v_mfma_f32_32x32x16_bf16 v[2:17], v[212:215], v[220:223], v[2:17]
	s_add_u32 m0, s65, 0xc000
	ds_read_b128 v[130:133], v154 offset:16
	global_load_lds_dwordx4 v160, s[66:67]
	v_mfma_f32_32x32x16_bf16 v[18:33], v[212:215], v[224:227], v[18:33]
	s_add_u32 m0, s65, 0xd000
	ds_read_b128 v[138:141], v156 offset:8208
	global_load_lds_dwordx4 v161, s[66:67]
	v_mfma_f32_32x32x16_bf16 v[34:49], v[216:219], v[220:223], v[34:49]
	s_add_u32 m0, s65, 0xe000
	ds_read_b128 v[142:145], v156 offset:10256
	global_load_lds_dwordx4 v160, s[12:13]
	v_mfma_f32_32x32x16_bf16 v[50:65], v[216:219], v[224:227], v[50:65]
	s_add_u32 m0, s65, 0xf000
	ds_read_b128 v[134:137], v154 offset:2064
	global_load_lds_dwordx4 v161, s[12:13]
	v_mfma_f32_32x32x16_bf16 v[66:81], v[212:215], v[228:231], v[66:81]
	s_add_u32 m0, s65, 0x10000
	ds_read_b128 v[146:149], v158 offset:8208
	global_load_lds_dwordx4 v160, s[62:63]
	v_mfma_f32_32x32x16_bf16 v[82:97], v[212:215], v[232:235], v[82:97]
	s_add_u32 m0, s65, 0x11000
	ds_read_b128 v[150:153], v158 offset:10256
	global_load_lds_dwordx4 v161, s[62:63]
	v_mfma_f32_32x32x16_bf16 v[98:113], v[216:219], v[228:231], v[98:113]
	s_add_u32 s66, s66, 64
	s_addc_u32 s67, s67, 0
	s_add_u32 s12, s12, 64
	s_addc_u32 s13, s13, 0
	v_mfma_f32_32x32x16_bf16 v[114:129], v[216:219], v[232:235], v[114:129]
	s_add_u32 s62, s62, 64
	s_addc_u32 s63, s63, 0
	s_sub_u32 s59, s59, 1
	s_cmp_lg_u32 s59, 0
	s_cbranch_scc1 .Lhw_ffnup_d_loop
	s_waitcnt lgkmcnt(4)
	v_mfma_f32_32x32x16_bf16 v[2:17], v[130:133], v[138:141], v[2:17]
	ds_read_b128 v[212:215], v155 offset:16
	s_waitcnt lgkmcnt(4)
	v_mfma_f32_32x32x16_bf16 v[18:33], v[130:133], v[142:145], v[18:33]
	ds_read_b128 v[220:223], v157 offset:8208
	s_waitcnt lgkmcnt(4)
	v_mfma_f32_32x32x16_bf16 v[34:49], v[134:137], v[138:141], v[34:49]
	ds_read_b128 v[224:227], v157 offset:10256
	s_waitcnt lgkmcnt(5)
	v_mfma_f32_32x32x16_bf16 v[50:65], v[134:137], v[142:145], v[50:65]
	ds_read_b128 v[216:219], v155 offset:2064
	s_waitcnt lgkmcnt(5)
	v_mfma_f32_32x32x16_bf16 v[66:81], v[130:133], v[146:149], v[66:81]
	ds_read_b128 v[228:231], v159 offset:8208
	s_waitcnt lgkmcnt(5)
	v_mfma_f32_32x32x16_bf16 v[82:97], v[130:133], v[150:153], v[82:97]
	ds_read_b128 v[232:235], v159 offset:10256
	s_waitcnt lgkmcnt(7)
	v_mfma_f32_32x32x16_bf16 v[98:113], v[134:137], v[146:149], v[98:113]
	s_waitcnt lgkmcnt(6)
	v_mfma_f32_32x32x16_bf16 v[114:129], v[134:137], v[150:153], v[114:129]
	s_waitcnt vmcnt(6) lgkmcnt(0)
	s_barrier
	v_mfma_f32_32x32x16_bf16 v[2:17], v[212:215], v[220:223], v[2:17]
	s_add_u32 m0, s65, 0x0
	ds_read_b128 v[130:133], v154 offset:24592
	global_load_lds_dwordx4 v160, s[66:67]
	v_mfma_f32_32x32x16_bf16 v[18:33], v[212:215], v[224:227], v[18:33]
	s_add_u32 m0, s65, 0x1000
	ds_read_b128 v[138:141], v156 offset:32784
	global_load_lds_dwordx4 v161, s[66:67]
	v_mfma_f32_32x32x16_bf16 v[34:49], v[216:219], v[220:223], v[34:49]
	s_add_u32 m0, s65, 0x2000
	ds_read_b128 v[142:145], v156 offset:34832
	global_load_lds_dwordx4 v160, s[12:13]
	v_mfma_f32_32x32x16_bf16 v[50:65], v[216:219], v[224:227], v[50:65]
	s_add_u32 m0, s65, 0x3000
	ds_read_b128 v[134:137], v154 offset:26640
	global_load_lds_dwordx4 v161, s[12:13]
	v_mfma_f32_32x32x16_bf16 v[66:81], v[212:215], v[228:231], v[66:81]
	s_add_u32 m0, s65, 0x4000
	ds_read_b128 v[146:149], v158 offset:32784
	global_load_lds_dwordx4 v160, s[62:63]
	v_mfma_f32_32x32x16_bf16 v[82:97], v[212:215], v[232:235], v[82:97]
	s_add_u32 m0, s65, 0x5000
	ds_read_b128 v[150:153], v158 offset:34832
	global_load_lds_dwordx4 v161, s[62:63]
	v_mfma_f32_32x32x16_bf16 v[98:113], v[216:219], v[228:231], v[98:113]
	s_add_u32 s66, s66, 64
	s_addc_u32 s67, s67, 0
	s_add_u32 s12, s12, 64
	s_addc_u32 s13, s13, 0
	v_mfma_f32_32x32x16_bf16 v[114:129], v[216:219], v[232:235], v[114:129]
	s_add_u32 s62, s62, 64
	s_addc_u32 s63, s63, 0
	s_waitcnt lgkmcnt(4)
	v_mfma_f32_32x32x16_bf16 v[2:17], v[130:133], v[138:141], v[2:17]
	ds_read_b128 v[212:215], v155 offset:24592
	s_waitcnt lgkmcnt(4)
	v_mfma_f32_32x32x16_bf16 v[18:33], v[130:133], v[142:145], v[18:33]
	ds_read_b128 v[220:223], v157 offset:32784
	s_waitcnt lgkmcnt(4)
	v_mfma_f32_32x32x16_bf16 v[34:49], v[134:137], v[138:141], v[34:49]
	ds_read_b128 v[224:227], v157 offset:34832
	s_waitcnt lgkmcnt(5)
	v_mfma_f32_32x32x16_bf16 v[50:65], v[134:137], v[142:145], v[50:65]
	ds_read_b128 v[216:219], v155 offset:26640
	s_waitcnt lgkmcnt(5)
	v_mfma_f32_32x32x16_bf16 v[66:81], v[130:133], v[146:149], v[66:81]
	ds_read_b128 v[228:231], v159 offset:32784
	s_waitcnt lgkmcnt(5)
	v_mfma_f32_32x32x16_bf16 v[82:97], v[130:133], v[150:153], v[82:97]
	ds_read_b128 v[232:235], v159 offset:34832
	s_waitcnt lgkmcnt(7)
	v_mfma_f32_32x32x16_bf16 v[98:113], v[134:137], v[146:149], v[98:113]
	s_waitcnt lgkmcnt(6)
	v_mfma_f32_32x32x16_bf16 v[114:129], v[134:137], v[150:153], v[114:129]
	s_waitcnt vmcnt(6) lgkmcnt(0)
	s_barrier
	v_mfma_f32_32x32x16_bf16 v[2:17], v[212:215], v[220:223], v[2:17]
	s_add_u32 m0, s65, 0x6000
	ds_read_b128 v[130:133], v154 offset:49168
	global_load_lds_dwordx4 v160, s[66:67]
	v_mfma_f32_32x32x16_bf16 v[18:33], v[212:215], v[224:227], v[18:33]
	s_add_u32 m0, s65, 0x7000
	ds_read_b128 v[138:141], v156 offset:57360
	global_load_lds_dwordx4 v161, s[66:67]
	v_mfma_f32_32x32x16_bf16 v[34:49], v[216:219], v[220:223], v[34:49]
	s_add_u32 m0, s65, 0x8000
	ds_read_b128 v[142:145], v156 offset:59408
	global_load_lds_dwordx4 v160, s[12:13]
	v_mfma_f32_32x32x16_bf16 v[50:65], v[216:219], v[224:227], v[50:65]
	s_add_u32 m0, s65, 0x9000
	ds_read_b128 v[134:137], v154 offset:51216
	global_load_lds_dwordx4 v161, s[12:13]
	v_mfma_f32_32x32x16_bf16 v[66:81], v[212:215], v[228:231], v[66:81]
	s_add_u32 m0, s65, 0xa000
	ds_read_b128 v[146:149], v158 offset:57360
	global_load_lds_dwordx4 v160, s[62:63]
	v_mfma_f32_32x32x16_bf16 v[82:97], v[212:215], v[232:235], v[82:97]
	s_add_u32 m0, s65, 0xb000
	ds_read_b128 v[150:153], v158 offset:59408
	global_load_lds_dwordx4 v161, s[62:63]
	v_mfma_f32_32x32x16_bf16 v[98:113], v[216:219], v[228:231], v[98:113]
	s_add_u32 s66, s66, 64
	s_addc_u32 s67, s67, 0
	s_add_u32 s12, s12, 64
	s_addc_u32 s13, s13, 0
	v_mfma_f32_32x32x16_bf16 v[114:129], v[216:219], v[232:235], v[114:129]
	s_add_u32 s62, s62, 64
	s_addc_u32 s63, s63, 0
	s_waitcnt lgkmcnt(4)
	v_mfma_f32_32x32x16_bf16 v[2:17], v[130:133], v[138:141], v[2:17]
	ds_read_b128 v[212:215], v155 offset:49168
	s_waitcnt lgkmcnt(4)
	v_mfma_f32_32x32x16_bf16 v[18:33], v[130:133], v[142:145], v[18:33]
	ds_read_b128 v[220:223], v157 offset:57360
	s_waitcnt lgkmcnt(4)
	v_mfma_f32_32x32x16_bf16 v[34:49], v[134:137], v[138:141], v[34:49]
	ds_read_b128 v[224:227], v157 offset:59408
	s_waitcnt lgkmcnt(5)
	v_mfma_f32_32x32x16_bf16 v[50:65], v[134:137], v[142:145], v[50:65]
	ds_read_b128 v[216:219], v155 offset:51216
	s_waitcnt lgkmcnt(5)
	v_mfma_f32_32x32x16_bf16 v[66:81], v[130:133], v[146:149], v[66:81]
	ds_read_b128 v[228:231], v159 offset:57360
	s_waitcnt lgkmcnt(5)
	v_mfma_f32_32x32x16_bf16 v[82:97], v[130:133], v[150:153], v[82:97]
	ds_read_b128 v[232:235], v159 offset:59408
	s_waitcnt lgkmcnt(7)
	v_mfma_f32_32x32x16_bf16 v[98:113], v[134:137], v[146:149], v[98:113]
	s_waitcnt lgkmcnt(6)
	v_mfma_f32_32x32x16_bf16 v[114:129], v[134:137], v[150:153], v[114:129]
	s_waitcnt vmcnt(6) lgkmcnt(0)
	s_barrier
	v_mfma_f32_32x32x16_bf16 v[2:17], v[212:215], v[220:223], v[2:17]
	ds_read_b128 v[130:133], v154 offset:16
	v_mfma_f32_32x32x16_bf16 v[18:33], v[212:215], v[224:227], v[18:33]
	ds_read_b128 v[138:141], v156 offset:8208
	v_mfma_f32_32x32x16_bf16 v[34:49], v[216:219], v[220:223], v[34:49]
	ds_read_b128 v[142:145], v156 offset:10256
	v_mfma_f32_32x32x16_bf16 v[50:65], v[216:219], v[224:227], v[50:65]
	ds_read_b128 v[134:137], v154 offset:2064
	v_mfma_f32_32x32x16_bf16 v[66:81], v[212:215], v[228:231], v[66:81]
	ds_read_b128 v[146:149], v158 offset:8208
	v_mfma_f32_32x32x16_bf16 v[82:97], v[212:215], v[232:235], v[82:97]
	ds_read_b128 v[150:153], v158 offset:10256
	v_mfma_f32_32x32x16_bf16 v[98:113], v[216:219], v[228:231], v[98:113]
	v_mfma_f32_32x32x16_bf16 v[114:129], v[216:219], v[232:235], v[114:129]
	s_waitcnt lgkmcnt(4)
	v_mfma_f32_32x32x16_bf16 v[2:17], v[130:133], v[138:141], v[2:17]
	ds_read_b128 v[212:215], v155 offset:16
	s_waitcnt lgkmcnt(4)
	v_mfma_f32_32x32x16_bf16 v[18:33], v[130:133], v[142:145], v[18:33]
	ds_read_b128 v[220:223], v157 offset:8208
	s_waitcnt lgkmcnt(4)
	v_mfma_f32_32x32x16_bf16 v[34:49], v[134:137], v[138:141], v[34:49]
	ds_read_b128 v[224:227], v157 offset:10256
	s_waitcnt lgkmcnt(5)
	v_mfma_f32_32x32x16_bf16 v[50:65], v[134:137], v[142:145], v[50:65]
	ds_read_b128 v[216:219], v155 offset:2064
	s_waitcnt lgkmcnt(5)
	v_mfma_f32_32x32x16_bf16 v[66:81], v[130:133], v[146:149], v[66:81]
	ds_read_b128 v[228:231], v159 offset:8208
	s_waitcnt lgkmcnt(5)
	v_mfma_f32_32x32x16_bf16 v[82:97], v[130:133], v[150:153], v[82:97]
	ds_read_b128 v[232:235], v159 offset:10256
	s_waitcnt lgkmcnt(7)
	v_mfma_f32_32x32x16_bf16 v[98:113], v[134:137], v[146:149], v[98:113]
	s_waitcnt lgkmcnt(6)
	v_mfma_f32_32x32x16_bf16 v[114:129], v[134:137], v[150:153], v[114:129]
	s_waitcnt vmcnt(0) lgkmcnt(0)
	s_barrier
	v_mfma_f32_32x32x16_bf16 v[2:17], v[212:215], v[220:223], v[2:17]
	ds_read_b128 v[130:133], v154 offset:24592
	v_mfma_f32_32x32x16_bf16 v[18:33], v[212:215], v[224:227], v[18:33]
	ds_read_b128 v[138:141], v156 offset:32784
	v_mfma_f32_32x32x16_bf16 v[34:49], v[216:219], v[220:223], v[34:49]
	ds_read_b128 v[142:145], v156 offset:34832
	v_mfma_f32_32x32x16_bf16 v[50:65], v[216:219], v[224:227], v[50:65]
	ds_read_b128 v[134:137], v154 offset:26640
	v_mfma_f32_32x32x16_bf16 v[66:81], v[212:215], v[228:231], v[66:81]
	ds_read_b128 v[146:149], v158 offset:32784
	v_mfma_f32_32x32x16_bf16 v[82:97], v[212:215], v[232:235], v[82:97]
	ds_read_b128 v[150:153], v158 offset:34832
	v_mfma_f32_32x32x16_bf16 v[98:113], v[216:219], v[228:231], v[98:113]
	v_mfma_f32_32x32x16_bf16 v[114:129], v[216:219], v[232:235], v[114:129]
	s_waitcnt lgkmcnt(4)
	v_mfma_f32_32x32x16_bf16 v[2:17], v[130:133], v[138:141], v[2:17]
	ds_read_b128 v[212:215], v155 offset:24592
	s_waitcnt lgkmcnt(4)
	v_mfma_f32_32x32x16_bf16 v[18:33], v[130:133], v[142:145], v[18:33]
	ds_read_b128 v[220:223], v157 offset:32784
	s_waitcnt lgkmcnt(4)
	v_mfma_f32_32x32x16_bf16 v[34:49], v[134:137], v[138:141], v[34:49]
	ds_read_b128 v[224:227], v157 offset:34832
	s_waitcnt lgkmcnt(5)
	v_mfma_f32_32x32x16_bf16 v[50:65], v[134:137], v[142:145], v[50:65]
	ds_read_b128 v[216:219], v155 offset:26640
	s_waitcnt lgkmcnt(5)
	v_mfma_f32_32x32x16_bf16 v[66:81], v[130:133], v[146:149], v[66:81]
	ds_read_b128 v[228:231], v159 offset:32784
	s_waitcnt lgkmcnt(5)
	v_mfma_f32_32x32x16_bf16 v[82:97], v[130:133], v[150:153], v[82:97]
	ds_read_b128 v[232:235], v159 offset:34832
	s_waitcnt lgkmcnt(7)
	v_mfma_f32_32x32x16_bf16 v[98:113], v[134:137], v[146:149], v[98:113]
	s_waitcnt lgkmcnt(6)
	v_mfma_f32_32x32x16_bf16 v[114:129], v[134:137], v[150:153], v[114:129]
	s_waitcnt lgkmcnt(0)
	v_mfma_f32_32x32x16_bf16 v[2:17], v[212:215], v[220:223], v[2:17]
	v_mfma_f32_32x32x16_bf16 v[18:33], v[212:215], v[224:227], v[18:33]
	v_mfma_f32_32x32x16_bf16 v[34:49], v[216:219], v[220:223], v[34:49]
	v_mfma_f32_32x32x16_bf16 v[50:65], v[216:219], v[224:227], v[50:65]
	v_mfma_f32_32x32x16_bf16 v[66:81], v[212:215], v[228:231], v[66:81]
	v_mfma_f32_32x32x16_bf16 v[82:97], v[212:215], v[232:235], v[82:97]
	v_mfma_f32_32x32x16_bf16 v[98:113], v[216:219], v[228:231], v[98:113]
	v_mfma_f32_32x32x16_bf16 v[114:129], v[216:219], v[232:235], v[114:129]
	s_nop 7
	s_nop 7
	s_mul_i32 vcc_lo, s6, 0x1600
	s_add_u32 s66, s8, vcc_lo
	s_addc_u32 s67, s9, 0
	s_add_u32 s66, s66, s14
	s_addc_u32 s67, s67, 0
	v_mul_f32_e32 v171, 0xbfb8aa3b, v2
	v_mul_f32_e32 v172, 0xbfb8aa3b, v3
	v_mul_f32_e32 v173, 0xbfb8aa3b, v4
	v_mul_f32_e32 v174, 0xbfb8aa3b, v5
	v_exp_f32_e32 v171, v171
	v_exp_f32_e32 v172, v172
	v_exp_f32_e32 v173, v173
	v_exp_f32_e32 v174, v174
	s_nop 0
	v_add_f32_e32 v171, 1.0, v171
	v_add_f32_e32 v172, 1.0, v172
	v_add_f32_e32 v173, 1.0, v173
	v_add_f32_e32 v174, 1.0, v174
	v_rcp_f32_e32 v171, v171
	v_rcp_f32_e32 v172, v172
	v_rcp_f32_e32 v173, v173
	v_rcp_f32_e32 v174, v174
	s_nop 0
	v_mul_f32_e32 v171, v2, v171
	v_mul_f32_e32 v172, v3, v172
	v_mul_f32_e32 v173, v4, v173
	v_mul_f32_e32 v174, v5, v174
	v_mul_f32_e32 v171, v18, v171
	v_mul_f32_e32 v172, v19, v172
	v_mul_f32_e32 v173, v20, v173
	v_mul_f32_e32 v174, v21, v174
	v_cvt_pk_bf16_f32 v179, v171, v171
	v_cvt_pk_bf16_f32 v180, v172, v172
	v_cvt_pk_bf16_f32 v181, v173, v173
	v_cvt_pk_bf16_f32 v182, v174, v174
	global_store_short v162, v179, s[66:67]
	global_store_short v163, v180, s[66:67]
	global_store_short v164, v181, s[66:67]
	global_store_short v165, v182, s[66:67]
	s_add_u32 s66, s66, 0xb000
	s_addc_u32 s67, s67, 0
	v_mul_f32_e32 v171, 0xbfb8aa3b, v6
	v_mul_f32_e32 v172, 0xbfb8aa3b, v7
	v_mul_f32_e32 v173, 0xbfb8aa3b, v8
	v_mul_f32_e32 v174, 0xbfb8aa3b, v9
	v_exp_f32_e32 v171, v171
	v_exp_f32_e32 v172, v172
	v_exp_f32_e32 v173, v173
	v_exp_f32_e32 v174, v174
	s_nop 0
	v_add_f32_e32 v171, 1.0, v171
	v_add_f32_e32 v172, 1.0, v172
	v_add_f32_e32 v173, 1.0, v173
	v_add_f32_e32 v174, 1.0, v174
	v_rcp_f32_e32 v171, v171
	v_rcp_f32_e32 v172, v172
	v_rcp_f32_e32 v173, v173
	v_rcp_f32_e32 v174, v174
	s_nop 0
	v_mul_f32_e32 v171, v6, v171
	v_mul_f32_e32 v172, v7, v172
	v_mul_f32_e32 v173, v8, v173
	v_mul_f32_e32 v174, v9, v174
	v_mul_f32_e32 v171, v22, v171
	v_mul_f32_e32 v172, v23, v172
	v_mul_f32_e32 v173, v24, v173
	v_mul_f32_e32 v174, v25, v174
	v_cvt_pk_bf16_f32 v179, v171, v171
	v_cvt_pk_bf16_f32 v180, v172, v172
	v_cvt_pk_bf16_f32 v181, v173, v173
	v_cvt_pk_bf16_f32 v182, v174, v174
	global_store_short v162, v179, s[66:67]
	global_store_short v163, v180, s[66:67]
	global_store_short v164, v181, s[66:67]
	global_store_short v165, v182, s[66:67]
	s_add_u32 s66, s66, 0xb000
	s_addc_u32 s67, s67, 0
	v_mul_f32_e32 v171, 0xbfb8aa3b, v10
	v_mul_f32_e32 v172, 0xbfb8aa3b, v11
	v_mul_f32_e32 v173, 0xbfb8aa3b, v12
	v_mul_f32_e32 v174, 0xbfb8aa3b, v13
	v_exp_f32_e32 v171, v171
	v_exp_f32_e32 v172, v172
	v_exp_f32_e32 v173, v173
	v_exp_f32_e32 v174, v174
	s_nop 0
	v_add_f32_e32 v171, 1.0, v171
	v_add_f32_e32 v172, 1.0, v172
	v_add_f32_e32 v173, 1.0, v173
	v_add_f32_e32 v174, 1.0, v174
	v_rcp_f32_e32 v171, v171
	v_rcp_f32_e32 v172, v172
	v_rcp_f32_e32 v173, v173
	v_rcp_f32_e32 v174, v174
	s_nop 0
	v_mul_f32_e32 v171, v10, v171
	v_mul_f32_e32 v172, v11, v172
	v_mul_f32_e32 v173, v12, v173
	v_mul_f32_e32 v174, v13, v174
	v_mul_f32_e32 v171, v26, v171
	v_mul_f32_e32 v172, v27, v172
	v_mul_f32_e32 v173, v28, v173
	v_mul_f32_e32 v174, v29, v174
	v_cvt_pk_bf16_f32 v179, v171, v171
	v_cvt_pk_bf16_f32 v180, v172, v172
	v_cvt_pk_bf16_f32 v181, v173, v173
	v_cvt_pk_bf16_f32 v182, v174, v174
	global_store_short v162, v179, s[66:67]
	global_store_short v163, v180, s[66:67]
	global_store_short v164, v181, s[66:67]
	global_store_short v165, v182, s[66:67]
	s_add_u32 s66, s66, 0xb000
	s_addc_u32 s67, s67, 0
	v_mul_f32_e32 v171, 0xbfb8aa3b, v14
	v_mul_f32_e32 v172, 0xbfb8aa3b, v15
	v_mul_f32_e32 v173, 0xbfb8aa3b, v16
	v_mul_f32_e32 v174, 0xbfb8aa3b, v17
	v_exp_f32_e32 v171, v171
	v_exp_f32_e32 v172, v172
	v_exp_f32_e32 v173, v173
	v_exp_f32_e32 v174, v174
	s_nop 0
	v_add_f32_e32 v171, 1.0, v171
	v_add_f32_e32 v172, 1.0, v172
	v_add_f32_e32 v173, 1.0, v173
	v_add_f32_e32 v174, 1.0, v174
	v_rcp_f32_e32 v171, v171
	v_rcp_f32_e32 v172, v172
	v_rcp_f32_e32 v173, v173
	v_rcp_f32_e32 v174, v174
	s_nop 0
	v_mul_f32_e32 v171, v14, v171
	v_mul_f32_e32 v172, v15, v172
	v_mul_f32_e32 v173, v16, v173
	v_mul_f32_e32 v174, v17, v174
	v_mul_f32_e32 v171, v30, v171
	v_mul_f32_e32 v172, v31, v172
	v_mul_f32_e32 v173, v32, v173
	v_mul_f32_e32 v174, v33, v174
	v_cvt_pk_bf16_f32 v179, v171, v171
	v_cvt_pk_bf16_f32 v180, v172, v172
	v_cvt_pk_bf16_f32 v181, v173, v173
	v_cvt_pk_bf16_f32 v182, v174, v174
	global_store_short v162, v179, s[66:67]
	global_store_short v163, v180, s[66:67]
	global_store_short v164, v181, s[66:67]
	global_store_short v165, v182, s[66:67]
	s_add_u32 s66, s66, 0xb000
	s_addc_u32 s67, s67, 0
	v_mul_f32_e32 v171, 0xbfb8aa3b, v34
	v_mul_f32_e32 v172, 0xbfb8aa3b, v35
	v_mul_f32_e32 v173, 0xbfb8aa3b, v36
	v_mul_f32_e32 v174, 0xbfb8aa3b, v37
	v_exp_f32_e32 v171, v171
	v_exp_f32_e32 v172, v172
	v_exp_f32_e32 v173, v173
	v_exp_f32_e32 v174, v174
	s_nop 0
	v_add_f32_e32 v171, 1.0, v171
	v_add_f32_e32 v172, 1.0, v172
	v_add_f32_e32 v173, 1.0, v173
	v_add_f32_e32 v174, 1.0, v174
	v_rcp_f32_e32 v171, v171
	v_rcp_f32_e32 v172, v172
	v_rcp_f32_e32 v173, v173
	v_rcp_f32_e32 v174, v174
	s_nop 0
	v_mul_f32_e32 v171, v34, v171
	v_mul_f32_e32 v172, v35, v172
	v_mul_f32_e32 v173, v36, v173
	v_mul_f32_e32 v174, v37, v174
	v_mul_f32_e32 v171, v50, v171
	v_mul_f32_e32 v172, v51, v172
	v_mul_f32_e32 v173, v52, v173
	v_mul_f32_e32 v174, v53, v174
	v_cvt_pk_bf16_f32 v179, v171, v171
	v_cvt_pk_bf16_f32 v180, v172, v172
	v_cvt_pk_bf16_f32 v181, v173, v173
	v_cvt_pk_bf16_f32 v182, v174, v174
	global_store_short v162, v179, s[66:67]
	global_store_short v163, v180, s[66:67]
	global_store_short v164, v181, s[66:67]
	global_store_short v165, v182, s[66:67]
	s_add_u32 s66, s66, 0xb000
	s_addc_u32 s67, s67, 0
	v_mul_f32_e32 v171, 0xbfb8aa3b, v38
	v_mul_f32_e32 v172, 0xbfb8aa3b, v39
	v_mul_f32_e32 v173, 0xbfb8aa3b, v40
	v_mul_f32_e32 v174, 0xbfb8aa3b, v41
	v_exp_f32_e32 v171, v171
	v_exp_f32_e32 v172, v172
	v_exp_f32_e32 v173, v173
	v_exp_f32_e32 v174, v174
	s_nop 0
	v_add_f32_e32 v171, 1.0, v171
	v_add_f32_e32 v172, 1.0, v172
	v_add_f32_e32 v173, 1.0, v173
	v_add_f32_e32 v174, 1.0, v174
	v_rcp_f32_e32 v171, v171
	v_rcp_f32_e32 v172, v172
	v_rcp_f32_e32 v173, v173
	v_rcp_f32_e32 v174, v174
	s_nop 0
	v_mul_f32_e32 v171, v38, v171
	v_mul_f32_e32 v172, v39, v172
	v_mul_f32_e32 v173, v40, v173
	v_mul_f32_e32 v174, v41, v174
	v_mul_f32_e32 v171, v54, v171
	v_mul_f32_e32 v172, v55, v172
	v_mul_f32_e32 v173, v56, v173
	v_mul_f32_e32 v174, v57, v174
	v_cvt_pk_bf16_f32 v179, v171, v171
	v_cvt_pk_bf16_f32 v180, v172, v172
	v_cvt_pk_bf16_f32 v181, v173, v173
	v_cvt_pk_bf16_f32 v182, v174, v174
	global_store_short v162, v179, s[66:67]
	global_store_short v163, v180, s[66:67]
	global_store_short v164, v181, s[66:67]
	global_store_short v165, v182, s[66:67]
	s_add_u32 s66, s66, 0xb000
	s_addc_u32 s67, s67, 0
	v_mul_f32_e32 v171, 0xbfb8aa3b, v42
	v_mul_f32_e32 v172, 0xbfb8aa3b, v43
	v_mul_f32_e32 v173, 0xbfb8aa3b, v44
	v_mul_f32_e32 v174, 0xbfb8aa3b, v45
	v_exp_f32_e32 v171, v171
	v_exp_f32_e32 v172, v172
	v_exp_f32_e32 v173, v173
	v_exp_f32_e32 v174, v174
	s_nop 0
	v_add_f32_e32 v171, 1.0, v171
	v_add_f32_e32 v172, 1.0, v172
	v_add_f32_e32 v173, 1.0, v173
	v_add_f32_e32 v174, 1.0, v174
	v_rcp_f32_e32 v171, v171
	v_rcp_f32_e32 v172, v172
	v_rcp_f32_e32 v173, v173
	v_rcp_f32_e32 v174, v174
	s_nop 0
	v_mul_f32_e32 v171, v42, v171
	v_mul_f32_e32 v172, v43, v172
	v_mul_f32_e32 v173, v44, v173
	v_mul_f32_e32 v174, v45, v174
	v_mul_f32_e32 v171, v58, v171
	v_mul_f32_e32 v172, v59, v172
	v_mul_f32_e32 v173, v60, v173
	v_mul_f32_e32 v174, v61, v174
	v_cvt_pk_bf16_f32 v179, v171, v171
	v_cvt_pk_bf16_f32 v180, v172, v172
	v_cvt_pk_bf16_f32 v181, v173, v173
	v_cvt_pk_bf16_f32 v182, v174, v174
	global_store_short v162, v179, s[66:67]
	global_store_short v163, v180, s[66:67]
	global_store_short v164, v181, s[66:67]
	global_store_short v165, v182, s[66:67]
	s_add_u32 s66, s66, 0xb000
	s_addc_u32 s67, s67, 0
	v_mul_f32_e32 v171, 0xbfb8aa3b, v46
	v_mul_f32_e32 v172, 0xbfb8aa3b, v47
	v_mul_f32_e32 v173, 0xbfb8aa3b, v48
	v_mul_f32_e32 v174, 0xbfb8aa3b, v49
	v_exp_f32_e32 v171, v171
	v_exp_f32_e32 v172, v172
	v_exp_f32_e32 v173, v173
	v_exp_f32_e32 v174, v174
	s_nop 0
	v_add_f32_e32 v171, 1.0, v171
	v_add_f32_e32 v172, 1.0, v172
	v_add_f32_e32 v173, 1.0, v173
	v_add_f32_e32 v174, 1.0, v174
	v_rcp_f32_e32 v171, v171
	v_rcp_f32_e32 v172, v172
	v_rcp_f32_e32 v173, v173
	v_rcp_f32_e32 v174, v174
	s_nop 0
	v_mul_f32_e32 v171, v46, v171
	v_mul_f32_e32 v172, v47, v172
	v_mul_f32_e32 v173, v48, v173
	v_mul_f32_e32 v174, v49, v174
	v_mul_f32_e32 v171, v62, v171
	v_mul_f32_e32 v172, v63, v172
	v_mul_f32_e32 v173, v64, v173
	v_mul_f32_e32 v174, v65, v174
	v_cvt_pk_bf16_f32 v179, v171, v171
	v_cvt_pk_bf16_f32 v180, v172, v172
	v_cvt_pk_bf16_f32 v181, v173, v173
	v_cvt_pk_bf16_f32 v182, v174, v174
	global_store_short v162, v179, s[66:67]
	global_store_short v163, v180, s[66:67]
	global_store_short v164, v181, s[66:67]
	global_store_short v165, v182, s[66:67]
	s_sub_u32 s66, s66, 0x4cf80
	s_subb_u32 s67, s67, 0
	v_mul_f32_e32 v171, 0xbfb8aa3b, v66
	v_mul_f32_e32 v172, 0xbfb8aa3b, v67
	v_mul_f32_e32 v173, 0xbfb8aa3b, v68
	v_mul_f32_e32 v174, 0xbfb8aa3b, v69
	v_exp_f32_e32 v171, v171
	v_exp_f32_e32 v172, v172
	v_exp_f32_e32 v173, v173
	v_exp_f32_e32 v174, v174
	s_nop 0
	v_add_f32_e32 v171, 1.0, v171
	v_add_f32_e32 v172, 1.0, v172
	v_add_f32_e32 v173, 1.0, v173
	v_add_f32_e32 v174, 1.0, v174
	v_rcp_f32_e32 v171, v171
	v_rcp_f32_e32 v172, v172
	v_rcp_f32_e32 v173, v173
	v_rcp_f32_e32 v174, v174
	s_nop 0
	v_mul_f32_e32 v171, v66, v171
	v_mul_f32_e32 v172, v67, v172
	v_mul_f32_e32 v173, v68, v173
	v_mul_f32_e32 v174, v69, v174
	v_mul_f32_e32 v171, v82, v171
	v_mul_f32_e32 v172, v83, v172
	v_mul_f32_e32 v173, v84, v173
	v_mul_f32_e32 v174, v85, v174
	v_cvt_pk_bf16_f32 v179, v171, v171
	v_cvt_pk_bf16_f32 v180, v172, v172
	v_cvt_pk_bf16_f32 v181, v173, v173
	v_cvt_pk_bf16_f32 v182, v174, v174
	global_store_short v162, v179, s[66:67]
	global_store_short v163, v180, s[66:67]
	global_store_short v164, v181, s[66:67]
	global_store_short v165, v182, s[66:67]
	s_add_u32 s66, s66, 0xb000
	s_addc_u32 s67, s67, 0
	v_mul_f32_e32 v171, 0xbfb8aa3b, v70
	v_mul_f32_e32 v172, 0xbfb8aa3b, v71
	v_mul_f32_e32 v173, 0xbfb8aa3b, v72
	v_mul_f32_e32 v174, 0xbfb8aa3b, v73
	v_exp_f32_e32 v171, v171
	v_exp_f32_e32 v172, v172
	v_exp_f32_e32 v173, v173
	v_exp_f32_e32 v174, v174
	s_nop 0
	v_add_f32_e32 v171, 1.0, v171
	v_add_f32_e32 v172, 1.0, v172
	v_add_f32_e32 v173, 1.0, v173
	v_add_f32_e32 v174, 1.0, v174
	v_rcp_f32_e32 v171, v171
	v_rcp_f32_e32 v172, v172
	v_rcp_f32_e32 v173, v173
	v_rcp_f32_e32 v174, v174
	s_nop 0
	v_mul_f32_e32 v171, v70, v171
	v_mul_f32_e32 v172, v71, v172
	v_mul_f32_e32 v173, v72, v173
	v_mul_f32_e32 v174, v73, v174
	v_mul_f32_e32 v171, v86, v171
	v_mul_f32_e32 v172, v87, v172
	v_mul_f32_e32 v173, v88, v173
	v_mul_f32_e32 v174, v89, v174
	v_cvt_pk_bf16_f32 v179, v171, v171
	v_cvt_pk_bf16_f32 v180, v172, v172
	v_cvt_pk_bf16_f32 v181, v173, v173
	v_cvt_pk_bf16_f32 v182, v174, v174
	global_store_short v162, v179, s[66:67]
	global_store_short v163, v180, s[66:67]
	global_store_short v164, v181, s[66:67]
	global_store_short v165, v182, s[66:67]
	s_add_u32 s66, s66, 0xb000
	s_addc_u32 s67, s67, 0
	v_mul_f32_e32 v171, 0xbfb8aa3b, v74
	v_mul_f32_e32 v172, 0xbfb8aa3b, v75
	v_mul_f32_e32 v173, 0xbfb8aa3b, v76
	v_mul_f32_e32 v174, 0xbfb8aa3b, v77
	v_exp_f32_e32 v171, v171
	v_exp_f32_e32 v172, v172
	v_exp_f32_e32 v173, v173
	v_exp_f32_e32 v174, v174
	s_nop 0
	v_add_f32_e32 v171, 1.0, v171
	v_add_f32_e32 v172, 1.0, v172
	v_add_f32_e32 v173, 1.0, v173
	v_add_f32_e32 v174, 1.0, v174
	v_rcp_f32_e32 v171, v171
	v_rcp_f32_e32 v172, v172
	v_rcp_f32_e32 v173, v173
	v_rcp_f32_e32 v174, v174
	s_nop 0
	v_mul_f32_e32 v171, v74, v171
	v_mul_f32_e32 v172, v75, v172
	v_mul_f32_e32 v173, v76, v173
	v_mul_f32_e32 v174, v77, v174
	v_mul_f32_e32 v171, v90, v171
	v_mul_f32_e32 v172, v91, v172
	v_mul_f32_e32 v173, v92, v173
	v_mul_f32_e32 v174, v93, v174
	v_cvt_pk_bf16_f32 v179, v171, v171
	v_cvt_pk_bf16_f32 v180, v172, v172
	v_cvt_pk_bf16_f32 v181, v173, v173
	v_cvt_pk_bf16_f32 v182, v174, v174
	global_store_short v162, v179, s[66:67]
	global_store_short v163, v180, s[66:67]
	global_store_short v164, v181, s[66:67]
	global_store_short v165, v182, s[66:67]
	s_add_u32 s66, s66, 0xb000
	s_addc_u32 s67, s67, 0
	v_mul_f32_e32 v171, 0xbfb8aa3b, v78
	v_mul_f32_e32 v172, 0xbfb8aa3b, v79
	v_mul_f32_e32 v173, 0xbfb8aa3b, v80
	v_mul_f32_e32 v174, 0xbfb8aa3b, v81
	v_exp_f32_e32 v171, v171
	v_exp_f32_e32 v172, v172
	v_exp_f32_e32 v173, v173
	v_exp_f32_e32 v174, v174
	s_nop 0
	v_add_f32_e32 v171, 1.0, v171
	v_add_f32_e32 v172, 1.0, v172
	v_add_f32_e32 v173, 1.0, v173
	v_add_f32_e32 v174, 1.0, v174
	v_rcp_f32_e32 v171, v171
	v_rcp_f32_e32 v172, v172
	v_rcp_f32_e32 v173, v173
	v_rcp_f32_e32 v174, v174
	s_nop 0
	v_mul_f32_e32 v171, v78, v171
	v_mul_f32_e32 v172, v79, v172
	v_mul_f32_e32 v173, v80, v173
	v_mul_f32_e32 v174, v81, v174
	v_mul_f32_e32 v171, v94, v171
	v_mul_f32_e32 v172, v95, v172
	v_mul_f32_e32 v173, v96, v173
	v_mul_f32_e32 v174, v97, v174
	v_cvt_pk_bf16_f32 v179, v171, v171
	v_cvt_pk_bf16_f32 v180, v172, v172
	v_cvt_pk_bf16_f32 v181, v173, v173
	v_cvt_pk_bf16_f32 v182, v174, v174
	global_store_short v162, v179, s[66:67]
	global_store_short v163, v180, s[66:67]
	global_store_short v164, v181, s[66:67]
	global_store_short v165, v182, s[66:67]
	s_add_u32 s66, s66, 0xb000
	s_addc_u32 s67, s67, 0
	v_mul_f32_e32 v171, 0xbfb8aa3b, v98
	v_mul_f32_e32 v172, 0xbfb8aa3b, v99
	v_mul_f32_e32 v173, 0xbfb8aa3b, v100
	v_mul_f32_e32 v174, 0xbfb8aa3b, v101
	v_exp_f32_e32 v171, v171
	v_exp_f32_e32 v172, v172
	v_exp_f32_e32 v173, v173
	v_exp_f32_e32 v174, v174
	s_nop 0
	v_add_f32_e32 v171, 1.0, v171
	v_add_f32_e32 v172, 1.0, v172
	v_add_f32_e32 v173, 1.0, v173
	v_add_f32_e32 v174, 1.0, v174
	v_rcp_f32_e32 v171, v171
	v_rcp_f32_e32 v172, v172
	v_rcp_f32_e32 v173, v173
	v_rcp_f32_e32 v174, v174
	s_nop 0
	v_mul_f32_e32 v171, v98, v171
	v_mul_f32_e32 v172, v99, v172
	v_mul_f32_e32 v173, v100, v173
	v_mul_f32_e32 v174, v101, v174
	v_mul_f32_e32 v171, v114, v171
	v_mul_f32_e32 v172, v115, v172
	v_mul_f32_e32 v173, v116, v173
	v_mul_f32_e32 v174, v117, v174
	v_cvt_pk_bf16_f32 v179, v171, v171
	v_cvt_pk_bf16_f32 v180, v172, v172
	v_cvt_pk_bf16_f32 v181, v173, v173
	v_cvt_pk_bf16_f32 v182, v174, v174
	global_store_short v162, v179, s[66:67]
	global_store_short v163, v180, s[66:67]
	global_store_short v164, v181, s[66:67]
	global_store_short v165, v182, s[66:67]
	s_add_u32 s66, s66, 0xb000
	s_addc_u32 s67, s67, 0
	v_mul_f32_e32 v171, 0xbfb8aa3b, v102
	v_mul_f32_e32 v172, 0xbfb8aa3b, v103
	v_mul_f32_e32 v173, 0xbfb8aa3b, v104
	v_mul_f32_e32 v174, 0xbfb8aa3b, v105
	v_exp_f32_e32 v171, v171
	v_exp_f32_e32 v172, v172
	v_exp_f32_e32 v173, v173
	v_exp_f32_e32 v174, v174
	s_nop 0
	v_add_f32_e32 v171, 1.0, v171
	v_add_f32_e32 v172, 1.0, v172
	v_add_f32_e32 v173, 1.0, v173
	v_add_f32_e32 v174, 1.0, v174
	v_rcp_f32_e32 v171, v171
	v_rcp_f32_e32 v172, v172
	v_rcp_f32_e32 v173, v173
	v_rcp_f32_e32 v174, v174
	s_nop 0
	v_mul_f32_e32 v171, v102, v171
	v_mul_f32_e32 v172, v103, v172
	v_mul_f32_e32 v173, v104, v173
	v_mul_f32_e32 v174, v105, v174
	v_mul_f32_e32 v171, v118, v171
	v_mul_f32_e32 v172, v119, v172
	v_mul_f32_e32 v173, v120, v173
	v_mul_f32_e32 v174, v121, v174
	v_cvt_pk_bf16_f32 v179, v171, v171
	v_cvt_pk_bf16_f32 v180, v172, v172
	v_cvt_pk_bf16_f32 v181, v173, v173
	v_cvt_pk_bf16_f32 v182, v174, v174
	global_store_short v162, v179, s[66:67]
	global_store_short v163, v180, s[66:67]
	global_store_short v164, v181, s[66:67]
	global_store_short v165, v182, s[66:67]
	s_add_u32 s66, s66, 0xb000
	s_addc_u32 s67, s67, 0
	v_mul_f32_e32 v171, 0xbfb8aa3b, v106
	v_mul_f32_e32 v172, 0xbfb8aa3b, v107
	v_mul_f32_e32 v173, 0xbfb8aa3b, v108
	v_mul_f32_e32 v174, 0xbfb8aa3b, v109
	v_exp_f32_e32 v171, v171
	v_exp_f32_e32 v172, v172
	v_exp_f32_e32 v173, v173
	v_exp_f32_e32 v174, v174
	s_nop 0
	v_add_f32_e32 v171, 1.0, v171
	v_add_f32_e32 v172, 1.0, v172
	v_add_f32_e32 v173, 1.0, v173
	v_add_f32_e32 v174, 1.0, v174
	v_rcp_f32_e32 v171, v171
	v_rcp_f32_e32 v172, v172
	v_rcp_f32_e32 v173, v173
	v_rcp_f32_e32 v174, v174
	s_nop 0
	v_mul_f32_e32 v171, v106, v171
	v_mul_f32_e32 v172, v107, v172
	v_mul_f32_e32 v173, v108, v173
	v_mul_f32_e32 v174, v109, v174
	v_mul_f32_e32 v171, v122, v171
	v_mul_f32_e32 v172, v123, v172
	v_mul_f32_e32 v173, v124, v173
	v_mul_f32_e32 v174, v125, v174
	v_cvt_pk_bf16_f32 v179, v171, v171
	v_cvt_pk_bf16_f32 v180, v172, v172
	v_cvt_pk_bf16_f32 v181, v173, v173
	v_cvt_pk_bf16_f32 v182, v174, v174
	global_store_short v162, v179, s[66:67]
	global_store_short v163, v180, s[66:67]
	global_store_short v164, v181, s[66:67]
	global_store_short v165, v182, s[66:67]
	s_add_u32 s66, s66, 0xb000
	s_addc_u32 s67, s67, 0
	v_mul_f32_e32 v171, 0xbfb8aa3b, v110
	v_mul_f32_e32 v172, 0xbfb8aa3b, v111
	v_mul_f32_e32 v173, 0xbfb8aa3b, v112
	v_mul_f32_e32 v174, 0xbfb8aa3b, v113
	v_exp_f32_e32 v171, v171
	v_exp_f32_e32 v172, v172
	v_exp_f32_e32 v173, v173
	v_exp_f32_e32 v174, v174
	s_nop 0
	v_add_f32_e32 v171, 1.0, v171
	v_add_f32_e32 v172, 1.0, v172
	v_add_f32_e32 v173, 1.0, v173
	v_add_f32_e32 v174, 1.0, v174
	v_rcp_f32_e32 v171, v171
	v_rcp_f32_e32 v172, v172
	v_rcp_f32_e32 v173, v173
	v_rcp_f32_e32 v174, v174
	s_nop 0
	v_mul_f32_e32 v171, v110, v171
	v_mul_f32_e32 v172, v111, v172
	v_mul_f32_e32 v173, v112, v173
	v_mul_f32_e32 v174, v113, v174
	v_mul_f32_e32 v171, v126, v171
	v_mul_f32_e32 v172, v127, v172
	v_mul_f32_e32 v173, v128, v173
	v_mul_f32_e32 v174, v129, v174
	v_cvt_pk_bf16_f32 v179, v171, v171
	v_cvt_pk_bf16_f32 v180, v172, v172
	v_cvt_pk_bf16_f32 v181, v173, v173
	v_cvt_pk_bf16_f32 v182, v174, v174
	global_store_short v162, v179, s[66:67]
	global_store_short v163, v180, s[66:67]
	global_store_short v164, v181, s[66:67]
	global_store_short v165, v182, s[66:67]
	v_readlane_b32 s62, v246, 14
	s_nop 0
	s_add_i32 s2, s2, s62
	s_branch .Lhw_ffnup_dloop

.Lhw_ffnup_sloop:
	s_sub_i32 s62, 0x108, s64
	s_lshl_b32 s62, s62, 1
	s_cmp_ge_u32 s2, s62
	s_cbranch_scc1 .Lhw_ffnup_exit
	s_lshr_b32 s63, s2, 1
	s_add_i32 s63, s63, s64
	s_mul_i32 s6, s63, 745
	s_lshr_b32 s6, s6, 16
	s_mul_i32 s14, s6, 88
	s_sub_i32 s14, s63, s14
	v_readlane_b32 s13, v246, 16
	s_lshl_b32 s6, s6, 2
	s_and_b32 s12, s14, 3
	s_add_i32 s6, s6, s12
	s_add_i32 s6, s6, s13
	s_lshl_b32 s6, s6, 7
	s_lshr_b32 s14, s14, 2
	s_lshl_b32 s14, s14, 8
	s_and_b32 s12, s2, 1
	s_lshl_b32 s12, s12, 7
	s_add_i32 s14, s14, s12
	s_lshl_b32 vcc_lo, s6, 11
	s_add_u32 s66, s10, vcc_lo
	s_addc_u32 s67, s11, 0
	s_lshl_b32 vcc_lo, s14, 11
	s_add_u32 s12, s0, vcc_lo
	s_addc_u32 s13, s1, 0
	s_barrier
	s_add_u32 m0, s65, 0x0
	s_nop 0
	global_load_lds_dwordx4 v160, s[66:67]
	s_add_u32 m0, s65, 0x1000
	s_nop 0
	global_load_lds_dwordx4 v161, s[66:67]
	s_add_u32 m0, s65, 0x2000
	s_nop 0
	global_load_lds_dwordx4 v160, s[12:13]
	s_add_u32 m0, s65, 0x3000
	s_nop 0
	global_load_lds_dwordx4 v161, s[12:13]
	s_add_u32 s66, s66, 64
	s_addc_u32 s67, s67, 0
	s_add_u32 s12, s12, 64
	s_addc_u32 s13, s13, 0
	s_add_u32 m0, s65, 0x6000
	s_nop 0
	global_load_lds_dwordx4 v160, s[66:67]
	s_add_u32 m0, s65, 0x7000
	s_nop 0
	global_load_lds_dwordx4 v161, s[66:67]
	s_add_u32 m0, s65, 0x8000
	s_nop 0
	global_load_lds_dwordx4 v160, s[12:13]
	s_add_u32 m0, s65, 0x9000
	s_nop 0
	global_load_lds_dwordx4 v161, s[12:13]
	s_add_u32 s66, s66, 64
	s_addc_u32 s67, s67, 0
	s_add_u32 s12, s12, 64
	s_addc_u32 s13, s13, 0
	s_add_u32 m0, s65, 0xc000
	s_nop 0
	global_load_lds_dwordx4 v160, s[66:67]
	s_add_u32 m0, s65, 0xd000
	s_nop 0
	global_load_lds_dwordx4 v161, s[66:67]
	s_add_u32 m0, s65, 0xe000
	s_nop 0
	global_load_lds_dwordx4 v160, s[12:13]
	s_add_u32 m0, s65, 0xf000
	s_nop 0
	global_load_lds_dwordx4 v161, s[12:13]
	s_add_u32 s66, s66, 64
	s_addc_u32 s67, s67, 0
	s_add_u32 s12, s12, 64
	s_addc_u32 s13, s13, 0
	v_mov_b32_e32 v2, 0
	v_mov_b32_e32 v3, 0
	v_mov_b32_e32 v4, 0
	v_mov_b32_e32 v5, 0
	v_mov_b32_e32 v6, 0
	v_mov_b32_e32 v7, 0
	v_mov_b32_e32 v8, 0
	v_mov_b32_e32 v9, 0
	v_mov_b32_e32 v10, 0
	v_mov_b32_e32 v11, 0
	v_mov_b32_e32 v12, 0
	v_mov_b32_e32 v13, 0
	v_mov_b32_e32 v14, 0
	v_mov_b32_e32 v15, 0
	v_mov_b32_e32 v16, 0
	v_mov_b32_e32 v17, 0
	v_mov_b32_e32 v18, 0
	v_mov_b32_e32 v19, 0
	v_mov_b32_e32 v20, 0
	v_mov_b32_e32 v21, 0
	v_mov_b32_e32 v22, 0
	v_mov_b32_e32 v23, 0
	v_mov_b32_e32 v24, 0
	v_mov_b32_e32 v25, 0
	v_mov_b32_e32 v26, 0
	v_mov_b32_e32 v27, 0
	v_mov_b32_e32 v28, 0
	v_mov_b32_e32 v29, 0
	v_mov_b32_e32 v30, 0
	v_mov_b32_e32 v31, 0
	v_mov_b32_e32 v32, 0
	v_mov_b32_e32 v33, 0
	v_mov_b32_e32 v34, 0
	v_mov_b32_e32 v35, 0
	v_mov_b32_e32 v36, 0
	v_mov_b32_e32 v37, 0
	v_mov_b32_e32 v38, 0
	v_mov_b32_e32 v39, 0
	v_mov_b32_e32 v40, 0
	v_mov_b32_e32 v41, 0
	v_mov_b32_e32 v42, 0
	v_mov_b32_e32 v43, 0
	v_mov_b32_e32 v44, 0
	v_mov_b32_e32 v45, 0
	v_mov_b32_e32 v46, 0
	v_mov_b32_e32 v47, 0
	v_mov_b32_e32 v48, 0
	v_mov_b32_e32 v49, 0
	v_mov_b32_e32 v50, 0
	v_mov_b32_e32 v51, 0
	v_mov_b32_e32 v52, 0
	v_mov_b32_e32 v53, 0
	v_mov_b32_e32 v54, 0
	v_mov_b32_e32 v55, 0
	v_mov_b32_e32 v56, 0
	v_mov_b32_e32 v57, 0
	v_mov_b32_e32 v58, 0
	v_mov_b32_e32 v59, 0
	v_mov_b32_e32 v60, 0
	v_mov_b32_e32 v61, 0
	v_mov_b32_e32 v62, 0
	v_mov_b32_e32 v63, 0
	v_mov_b32_e32 v64, 0
	v_mov_b32_e32 v65, 0
	s_waitcnt vmcnt(8)
	s_barrier
	ds_read_b128 v[130:133], v154 offset:16
	ds_read_b128 v[138:141], v156 offset:8208
	ds_read_b128 v[142:145], v156 offset:10256
	ds_read_b128 v[134:137], v154 offset:2064
	s_mov_b32 s59, 9
.Lhw_ffnup_s_loop:
	s_waitcnt lgkmcnt(2)
	v_mfma_f32_32x32x16_bf16 v[2:17], v[130:133], v[138:141], v[2:17]
	ds_read_b128 v[212:215], v155 offset:16
	s_waitcnt lgkmcnt(2)
	v_mfma_f32_32x32x16_bf16 v[18:33], v[130:133], v[142:145], v[18:33]
	ds_read_b128 v[220:223], v157 offset:8208
	s_waitcnt lgkmcnt(2)
	v_mfma_f32_32x32x16_bf16 v[34:49], v[134:137], v[138:141], v[34:49]
	ds_read_b128 v[224:227], v157 offset:10256
	s_waitcnt lgkmcnt(3)
	v_mfma_f32_32x32x16_bf16 v[50:65], v[134:137], v[142:145], v[50:65]
	ds_read_b128 v[216:219], v155 offset:2064
	s_waitcnt vmcnt(4) lgkmcnt(0)
	s_barrier
	v_mfma_f32_32x32x16_bf16 v[2:17], v[212:215], v[220:223], v[2:17]
	s_add_u32 m0, s65, 0x0
	ds_read_b128 v[130:133], v154 offset:24592
	global_load_lds_dwordx4 v160, s[66:67]
	v_mfma_f32_32x32x16_bf16 v[18:33], v[212:215], v[224:227], v[18:33]
	s_add_u32 m0, s65, 0x1000
	ds_read_b128 v[138:141], v156 offset:32784
	global_load_lds_dwordx4 v161, s[66:67]
	v_mfma_f32_32x32x16_bf16 v[34:49], v[216:219], v[220:223], v[34:49]
	s_add_u32 m0, s65, 0x2000
	ds_read_b128 v[142:145], v156 offset:34832
	global_load_lds_dwordx4 v160, s[12:13]
	v_mfma_f32_32x32x16_bf16 v[50:65], v[216:219], v[224:227], v[50:65]
	s_add_u32 m0, s65, 0x3000
	ds_read_b128 v[134:137], v154 offset:26640
	global_load_lds_dwordx4 v161, s[12:13]
	s_add_u32 s66, s66, 64
	s_addc_u32 s67, s67, 0
	s_add_u32 s12, s12, 64
	s_addc_u32 s13, s13, 0
	s_waitcnt lgkmcnt(2)
	v_mfma_f32_32x32x16_bf16 v[2:17], v[130:133], v[138:141], v[2:17]
	ds_read_b128 v[212:215], v155 offset:24592
	s_waitcnt lgkmcnt(2)
	v_mfma_f32_32x32x16_bf16 v[18:33], v[130:133], v[142:145], v[18:33]
	ds_read_b128 v[220:223], v157 offset:32784
	s_waitcnt lgkmcnt(2)
	v_mfma_f32_32x32x16_bf16 v[34:49], v[134:137], v[138:141], v[34:49]
	ds_read_b128 v[224:227], v157 offset:34832
	s_waitcnt lgkmcnt(3)
	v_mfma_f32_32x32x16_bf16 v[50:65], v[134:137], v[142:145], v[50:65]
	ds_read_b128 v[216:219], v155 offset:26640
	s_waitcnt vmcnt(4) lgkmcnt(0)
	s_barrier
	v_mfma_f32_32x32x16_bf16 v[2:17], v[212:215], v[220:223], v[2:17]
	s_add_u32 m0, s65, 0x6000
	ds_read_b128 v[130:133], v154 offset:49168
	global_load_lds_dwordx4 v160, s[66:67]
	v_mfma_f32_32x32x16_bf16 v[18:33], v[212:215], v[224:227], v[18:33]
	s_add_u32 m0, s65, 0x7000
	ds_read_b128 v[138:141], v156 offset:57360
	global_load_lds_dwordx4 v161, s[66:67]
	v_mfma_f32_32x32x16_bf16 v[34:49], v[216:219], v[220:223], v[34:49]
	s_add_u32 m0, s65, 0x8000
	ds_read_b128 v[142:145], v156 offset:59408
	global_load_lds_dwordx4 v160, s[12:13]
	v_mfma_f32_32x32x16_bf16 v[50:65], v[216:219], v[224:227], v[50:65]
	s_add_u32 m0, s65, 0x9000
	ds_read_b128 v[134:137], v154 offset:51216
	global_load_lds_dwordx4 v161, s[12:13]
	s_add_u32 s66, s66, 64
	s_addc_u32 s67, s67, 0
	s_add_u32 s12, s12, 64
	s_addc_u32 s13, s13, 0
	s_waitcnt lgkmcnt(2)
	v_mfma_f32_32x32x16_bf16 v[2:17], v[130:133], v[138:141], v[2:17]
	ds_read_b128 v[212:215], v155 offset:49168
	s_waitcnt lgkmcnt(2)
	v_mfma_f32_32x32x16_bf16 v[18:33], v[130:133], v[142:145], v[18:33]
	ds_read_b128 v[220:223], v157 offset:57360
	s_waitcnt lgkmcnt(2)
	v_mfma_f32_32x32x16_bf16 v[34:49], v[134:137], v[138:141], v[34:49]
	ds_read_b128 v[224:227], v157 offset:59408
	s_waitcnt lgkmcnt(3)
	v_mfma_f32_32x32x16_bf16 v[50:65], v[134:137], v[142:145], v[50:65]
	ds_read_b128 v[216:219], v155 offset:51216
	s_waitcnt vmcnt(4) lgkmcnt(0)
	s_barrier
	v_mfma_f32_32x32x16_bf16 v[2:17], v[212:215], v[220:223], v[2:17]
	s_add_u32 m0, s65, 0xc000
	ds_read_b128 v[130:133], v154 offset:16
	global_load_lds_dwordx4 v160, s[66:67]
	v_mfma_f32_32x32x16_bf16 v[18:33], v[212:215], v[224:227], v[18:33]
	s_add_u32 m0, s65, 0xd000
	ds_read_b128 v[138:141], v156 offset:8208
	global_load_lds_dwordx4 v161, s[66:67]
	v_mfma_f32_32x32x16_bf16 v[34:49], v[216:219], v[220:223], v[34:49]
	s_add_u32 m0, s65, 0xe000
	ds_read_b128 v[142:145], v156 offset:10256
	global_load_lds_dwordx4 v160, s[12:13]
	v_mfma_f32_32x32x16_bf16 v[50:65], v[216:219], v[224:227], v[50:65]
	s_add_u32 m0, s65, 0xf000
	ds_read_b128 v[134:137], v154 offset:2064
	global_load_lds_dwordx4 v161, s[12:13]
	s_add_u32 s66, s66, 64
	s_addc_u32 s67, s67, 0
	s_add_u32 s12, s12, 64
	s_addc_u32 s13, s13, 0
	s_sub_u32 s59, s59, 1
	s_cmp_lg_u32 s59, 0
	s_cbranch_scc1 .Lhw_ffnup_s_loop
	s_waitcnt lgkmcnt(2)
	v_mfma_f32_32x32x16_bf16 v[2:17], v[130:133], v[138:141], v[2:17]
	ds_read_b128 v[212:215], v155 offset:16
	s_waitcnt lgkmcnt(2)
	v_mfma_f32_32x32x16_bf16 v[18:33], v[130:133], v[142:145], v[18:33]
	ds_read_b128 v[220:223], v157 offset:8208
	s_waitcnt lgkmcnt(2)
	v_mfma_f32_32x32x16_bf16 v[34:49], v[134:137], v[138:141], v[34:49]
	ds_read_b128 v[224:227], v157 offset:10256
	s_waitcnt lgkmcnt(3)
	v_mfma_f32_32x32x16_bf16 v[50:65], v[134:137], v[142:145], v[50:65]
	ds_read_b128 v[216:219], v155 offset:2064
	s_waitcnt vmcnt(4) lgkmcnt(0)
	s_barrier
	v_mfma_f32_32x32x16_bf16 v[2:17], v[212:215], v[220:223], v[2:17]
	s_add_u32 m0, s65, 0x0
	ds_read_b128 v[130:133], v154 offset:24592
	global_load_lds_dwordx4 v160, s[66:67]
	v_mfma_f32_32x32x16_bf16 v[18:33], v[212:215], v[224:227], v[18:33]
	s_add_u32 m0, s65, 0x1000
	ds_read_b128 v[138:141], v156 offset:32784
	global_load_lds_dwordx4 v161, s[66:67]
	v_mfma_f32_32x32x16_bf16 v[34:49], v[216:219], v[220:223], v[34:49]
	s_add_u32 m0, s65, 0x2000
	ds_read_b128 v[142:145], v156 offset:34832
	global_load_lds_dwordx4 v160, s[12:13]
	v_mfma_f32_32x32x16_bf16 v[50:65], v[216:219], v[224:227], v[50:65]
	s_add_u32 m0, s65, 0x3000
	ds_read_b128 v[134:137], v154 offset:26640
	global_load_lds_dwordx4 v161, s[12:13]
	s_add_u32 s66, s66, 64
	s_addc_u32 s67, s67, 0
	s_add_u32 s12, s12, 64
	s_addc_u32 s13, s13, 0
	s_waitcnt lgkmcnt(2)
	v_mfma_f32_32x32x16_bf16 v[2:17], v[130:133], v[138:141], v[2:17]
	ds_read_b128 v[212:215], v155 offset:24592
	s_waitcnt lgkmcnt(2)
	v_mfma_f32_32x32x16_bf16 v[18:33], v[130:133], v[142:145], v[18:33]
	ds_read_b128 v[220:223], v157 offset:32784
	s_waitcnt lgkmcnt(2)
	v_mfma_f32_32x32x16_bf16 v[34:49], v[134:137], v[138:141], v[34:49]
	ds_read_b128 v[224:227], v157 offset:34832
	s_waitcnt lgkmcnt(3)
	v_mfma_f32_32x32x16_bf16 v[50:65], v[134:137], v[142:145], v[50:65]
	ds_read_b128 v[216:219], v155 offset:26640
	s_waitcnt vmcnt(4) lgkmcnt(0)
	s_barrier
	v_mfma_f32_32x32x16_bf16 v[2:17], v[212:215], v[220:223], v[2:17]
	s_add_u32 m0, s65, 0x6000
	ds_read_b128 v[130:133], v154 offset:49168
	global_load_lds_dwordx4 v160, s[66:67]
	v_mfma_f32_32x32x16_bf16 v[18:33], v[212:215], v[224:227], v[18:33]
	s_add_u32 m0, s65, 0x7000
	ds_read_b128 v[138:141], v156 offset:57360
	global_load_lds_dwordx4 v161, s[66:67]
	v_mfma_f32_32x32x16_bf16 v[34:49], v[216:219], v[220:223], v[34:49]
	s_add_u32 m0, s65, 0x8000
	ds_read_b128 v[142:145], v156 offset:59408
	global_load_lds_dwordx4 v160, s[12:13]
	v_mfma_f32_32x32x16_bf16 v[50:65], v[216:219], v[224:227], v[50:65]
	s_add_u32 m0, s65, 0x9000
	ds_read_b128 v[134:137], v154 offset:51216
	global_load_lds_dwordx4 v161, s[12:13]
	s_add_u32 s66, s66, 64
	s_addc_u32 s67, s67, 0
	s_add_u32 s12, s12, 64
	s_addc_u32 s13, s13, 0
	s_waitcnt lgkmcnt(2)
	v_mfma_f32_32x32x16_bf16 v[2:17], v[130:133], v[138:141], v[2:17]
	ds_read_b128 v[212:215], v155 offset:49168
	s_waitcnt lgkmcnt(2)
	v_mfma_f32_32x32x16_bf16 v[18:33], v[130:133], v[142:145], v[18:33]
	ds_read_b128 v[220:223], v157 offset:57360
	s_waitcnt lgkmcnt(2)
	v_mfma_f32_32x32x16_bf16 v[34:49], v[134:137], v[138:141], v[34:49]
	ds_read_b128 v[224:227], v157 offset:59408
	s_waitcnt lgkmcnt(3)
	v_mfma_f32_32x32x16_bf16 v[50:65], v[134:137], v[142:145], v[50:65]
	ds_read_b128 v[216:219], v155 offset:51216
	s_waitcnt vmcnt(4) lgkmcnt(0)
	s_barrier
	v_mfma_f32_32x32x16_bf16 v[2:17], v[212:215], v[220:223], v[2:17]
	ds_read_b128 v[130:133], v154 offset:16
	v_mfma_f32_32x32x16_bf16 v[18:33], v[212:215], v[224:227], v[18:33]
	ds_read_b128 v[138:141], v156 offset:8208
	v_mfma_f32_32x32x16_bf16 v[34:49], v[216:219], v[220:223], v[34:49]
	ds_read_b128 v[142:145], v156 offset:10256
	v_mfma_f32_32x32x16_bf16 v[50:65], v[216:219], v[224:227], v[50:65]
	ds_read_b128 v[134:137], v154 offset:2064
	s_waitcnt lgkmcnt(2)
	v_mfma_f32_32x32x16_bf16 v[2:17], v[130:133], v[138:141], v[2:17]
	ds_read_b128 v[212:215], v155 offset:16
	s_waitcnt lgkmcnt(2)
	v_mfma_f32_32x32x16_bf16 v[18:33], v[130:133], v[142:145], v[18:33]
	ds_read_b128 v[220:223], v157 offset:8208
	s_waitcnt lgkmcnt(2)
	v_mfma_f32_32x32x16_bf16 v[34:49], v[134:137], v[138:141], v[34:49]
	ds_read_b128 v[224:227], v157 offset:10256
	s_waitcnt lgkmcnt(3)
	v_mfma_f32_32x32x16_bf16 v[50:65], v[134:137], v[142:145], v[50:65]
	ds_read_b128 v[216:219], v155 offset:2064
	s_waitcnt vmcnt(0) lgkmcnt(0)
	s_barrier
	v_mfma_f32_32x32x16_bf16 v[2:17], v[212:215], v[220:223], v[2:17]
	ds_read_b128 v[130:133], v154 offset:24592
	v_mfma_f32_32x32x16_bf16 v[18:33], v[212:215], v[224:227], v[18:33]
	ds_read_b128 v[138:141], v156 offset:32784
	v_mfma_f32_32x32x16_bf16 v[34:49], v[216:219], v[220:223], v[34:49]
	ds_read_b128 v[142:145], v156 offset:34832
	v_mfma_f32_32x32x16_bf16 v[50:65], v[216:219], v[224:227], v[50:65]
	ds_read_b128 v[134:137], v154 offset:26640
	s_waitcnt lgkmcnt(2)
	v_mfma_f32_32x32x16_bf16 v[2:17], v[130:133], v[138:141], v[2:17]
	ds_read_b128 v[212:215], v155 offset:24592
	s_waitcnt lgkmcnt(2)
	v_mfma_f32_32x32x16_bf16 v[18:33], v[130:133], v[142:145], v[18:33]
	ds_read_b128 v[220:223], v157 offset:32784
	s_waitcnt lgkmcnt(2)
	v_mfma_f32_32x32x16_bf16 v[34:49], v[134:137], v[138:141], v[34:49]
	ds_read_b128 v[224:227], v157 offset:34832
	s_waitcnt lgkmcnt(3)
	v_mfma_f32_32x32x16_bf16 v[50:65], v[134:137], v[142:145], v[50:65]
	ds_read_b128 v[216:219], v155 offset:26640
	s_waitcnt lgkmcnt(0)
	v_mfma_f32_32x32x16_bf16 v[2:17], v[212:215], v[220:223], v[2:17]
	v_mfma_f32_32x32x16_bf16 v[18:33], v[212:215], v[224:227], v[18:33]
	v_mfma_f32_32x32x16_bf16 v[34:49], v[216:219], v[220:223], v[34:49]
	v_mfma_f32_32x32x16_bf16 v[50:65], v[216:219], v[224:227], v[50:65]
	s_nop 7
	s_nop 7
	s_mul_i32 vcc_lo, s6, 0x1600
	s_add_u32 s66, s8, vcc_lo
	s_addc_u32 s67, s9, 0
	s_add_u32 s66, s66, s14
	s_addc_u32 s67, s67, 0
	v_mul_f32_e32 v171, 0xbfb8aa3b, v2
	v_mul_f32_e32 v172, 0xbfb8aa3b, v3
	v_mul_f32_e32 v173, 0xbfb8aa3b, v4
	v_mul_f32_e32 v174, 0xbfb8aa3b, v5
	v_exp_f32_e32 v171, v171
	v_exp_f32_e32 v172, v172
	v_exp_f32_e32 v173, v173
	v_exp_f32_e32 v174, v174
	s_nop 0
	v_add_f32_e32 v171, 1.0, v171
	v_add_f32_e32 v172, 1.0, v172
	v_add_f32_e32 v173, 1.0, v173
	v_add_f32_e32 v174, 1.0, v174
	v_rcp_f32_e32 v171, v171
	v_rcp_f32_e32 v172, v172
	v_rcp_f32_e32 v173, v173
	v_rcp_f32_e32 v174, v174
	s_nop 0
	v_mul_f32_e32 v171, v2, v171
	v_mul_f32_e32 v172, v3, v172
	v_mul_f32_e32 v173, v4, v173
	v_mul_f32_e32 v174, v5, v174
	v_mul_f32_e32 v171, v18, v171
	v_mul_f32_e32 v172, v19, v172
	v_mul_f32_e32 v173, v20, v173
	v_mul_f32_e32 v174, v21, v174
	v_cvt_pk_bf16_f32 v179, v171, v171
	v_cvt_pk_bf16_f32 v180, v172, v172
	v_cvt_pk_bf16_f32 v181, v173, v173
	v_cvt_pk_bf16_f32 v182, v174, v174
	global_store_short v162, v179, s[66:67]
	global_store_short v163, v180, s[66:67]
	global_store_short v164, v181, s[66:67]
	global_store_short v165, v182, s[66:67]
	s_add_u32 s66, s66, 0xb000
	s_addc_u32 s67, s67, 0
	v_mul_f32_e32 v171, 0xbfb8aa3b, v6
	v_mul_f32_e32 v172, 0xbfb8aa3b, v7
	v_mul_f32_e32 v173, 0xbfb8aa3b, v8
	v_mul_f32_e32 v174, 0xbfb8aa3b, v9
	v_exp_f32_e32 v171, v171
	v_exp_f32_e32 v172, v172
	v_exp_f32_e32 v173, v173
	v_exp_f32_e32 v174, v174
	s_nop 0
	v_add_f32_e32 v171, 1.0, v171
	v_add_f32_e32 v172, 1.0, v172
	v_add_f32_e32 v173, 1.0, v173
	v_add_f32_e32 v174, 1.0, v174
	v_rcp_f32_e32 v171, v171
	v_rcp_f32_e32 v172, v172
	v_rcp_f32_e32 v173, v173
	v_rcp_f32_e32 v174, v174
	s_nop 0
	v_mul_f32_e32 v171, v6, v171
	v_mul_f32_e32 v172, v7, v172
	v_mul_f32_e32 v173, v8, v173
	v_mul_f32_e32 v174, v9, v174
	v_mul_f32_e32 v171, v22, v171
	v_mul_f32_e32 v172, v23, v172
	v_mul_f32_e32 v173, v24, v173
	v_mul_f32_e32 v174, v25, v174
	v_cvt_pk_bf16_f32 v179, v171, v171
	v_cvt_pk_bf16_f32 v180, v172, v172
	v_cvt_pk_bf16_f32 v181, v173, v173
	v_cvt_pk_bf16_f32 v182, v174, v174
	global_store_short v162, v179, s[66:67]
	global_store_short v163, v180, s[66:67]
	global_store_short v164, v181, s[66:67]
	global_store_short v165, v182, s[66:67]
	s_add_u32 s66, s66, 0xb000
	s_addc_u32 s67, s67, 0
	v_mul_f32_e32 v171, 0xbfb8aa3b, v10
	v_mul_f32_e32 v172, 0xbfb8aa3b, v11
	v_mul_f32_e32 v173, 0xbfb8aa3b, v12
	v_mul_f32_e32 v174, 0xbfb8aa3b, v13
	v_exp_f32_e32 v171, v171
	v_exp_f32_e32 v172, v172
	v_exp_f32_e32 v173, v173
	v_exp_f32_e32 v174, v174
	s_nop 0
	v_add_f32_e32 v171, 1.0, v171
	v_add_f32_e32 v172, 1.0, v172
	v_add_f32_e32 v173, 1.0, v173
	v_add_f32_e32 v174, 1.0, v174
	v_rcp_f32_e32 v171, v171
	v_rcp_f32_e32 v172, v172
	v_rcp_f32_e32 v173, v173
	v_rcp_f32_e32 v174, v174
	s_nop 0
	v_mul_f32_e32 v171, v10, v171
	v_mul_f32_e32 v172, v11, v172
	v_mul_f32_e32 v173, v12, v173
	v_mul_f32_e32 v174, v13, v174
	v_mul_f32_e32 v171, v26, v171
	v_mul_f32_e32 v172, v27, v172
	v_mul_f32_e32 v173, v28, v173
	v_mul_f32_e32 v174, v29, v174
	v_cvt_pk_bf16_f32 v179, v171, v171
	v_cvt_pk_bf16_f32 v180, v172, v172
	v_cvt_pk_bf16_f32 v181, v173, v173
	v_cvt_pk_bf16_f32 v182, v174, v174
	global_store_short v162, v179, s[66:67]
	global_store_short v163, v180, s[66:67]
	global_store_short v164, v181, s[66:67]
	global_store_short v165, v182, s[66:67]
	s_add_u32 s66, s66, 0xb000
	s_addc_u32 s67, s67, 0
	v_mul_f32_e32 v171, 0xbfb8aa3b, v14
	v_mul_f32_e32 v172, 0xbfb8aa3b, v15
	v_mul_f32_e32 v173, 0xbfb8aa3b, v16
	v_mul_f32_e32 v174, 0xbfb8aa3b, v17
	v_exp_f32_e32 v171, v171
	v_exp_f32_e32 v172, v172
	v_exp_f32_e32 v173, v173
	v_exp_f32_e32 v174, v174
	s_nop 0
	v_add_f32_e32 v171, 1.0, v171
	v_add_f32_e32 v172, 1.0, v172
	v_add_f32_e32 v173, 1.0, v173
	v_add_f32_e32 v174, 1.0, v174
	v_rcp_f32_e32 v171, v171
	v_rcp_f32_e32 v172, v172
	v_rcp_f32_e32 v173, v173
	v_rcp_f32_e32 v174, v174
	s_nop 0
	v_mul_f32_e32 v171, v14, v171
	v_mul_f32_e32 v172, v15, v172
	v_mul_f32_e32 v173, v16, v173
	v_mul_f32_e32 v174, v17, v174
	v_mul_f32_e32 v171, v30, v171
	v_mul_f32_e32 v172, v31, v172
	v_mul_f32_e32 v173, v32, v173
	v_mul_f32_e32 v174, v33, v174
	v_cvt_pk_bf16_f32 v179, v171, v171
	v_cvt_pk_bf16_f32 v180, v172, v172
	v_cvt_pk_bf16_f32 v181, v173, v173
	v_cvt_pk_bf16_f32 v182, v174, v174
	global_store_short v162, v179, s[66:67]
	global_store_short v163, v180, s[66:67]
	global_store_short v164, v181, s[66:67]
	global_store_short v165, v182, s[66:67]
	s_add_u32 s66, s66, 0xb000
	s_addc_u32 s67, s67, 0
	v_mul_f32_e32 v171, 0xbfb8aa3b, v34
	v_mul_f32_e32 v172, 0xbfb8aa3b, v35
	v_mul_f32_e32 v173, 0xbfb8aa3b, v36
	v_mul_f32_e32 v174, 0xbfb8aa3b, v37
	v_exp_f32_e32 v171, v171
	v_exp_f32_e32 v172, v172
	v_exp_f32_e32 v173, v173
	v_exp_f32_e32 v174, v174
	s_nop 0
	v_add_f32_e32 v171, 1.0, v171
	v_add_f32_e32 v172, 1.0, v172
	v_add_f32_e32 v173, 1.0, v173
	v_add_f32_e32 v174, 1.0, v174
	v_rcp_f32_e32 v171, v171
	v_rcp_f32_e32 v172, v172
	v_rcp_f32_e32 v173, v173
	v_rcp_f32_e32 v174, v174
	s_nop 0
	v_mul_f32_e32 v171, v34, v171
	v_mul_f32_e32 v172, v35, v172
	v_mul_f32_e32 v173, v36, v173
	v_mul_f32_e32 v174, v37, v174
	v_mul_f32_e32 v171, v50, v171
	v_mul_f32_e32 v172, v51, v172
	v_mul_f32_e32 v173, v52, v173
	v_mul_f32_e32 v174, v53, v174
	v_cvt_pk_bf16_f32 v179, v171, v171
	v_cvt_pk_bf16_f32 v180, v172, v172
	v_cvt_pk_bf16_f32 v181, v173, v173
	v_cvt_pk_bf16_f32 v182, v174, v174
	global_store_short v162, v179, s[66:67]
	global_store_short v163, v180, s[66:67]
	global_store_short v164, v181, s[66:67]
	global_store_short v165, v182, s[66:67]
	s_add_u32 s66, s66, 0xb000
	s_addc_u32 s67, s67, 0
	v_mul_f32_e32 v171, 0xbfb8aa3b, v38
	v_mul_f32_e32 v172, 0xbfb8aa3b, v39
	v_mul_f32_e32 v173, 0xbfb8aa3b, v40
	v_mul_f32_e32 v174, 0xbfb8aa3b, v41
	v_exp_f32_e32 v171, v171
	v_exp_f32_e32 v172, v172
	v_exp_f32_e32 v173, v173
	v_exp_f32_e32 v174, v174
	s_nop 0
	v_add_f32_e32 v171, 1.0, v171
	v_add_f32_e32 v172, 1.0, v172
	v_add_f32_e32 v173, 1.0, v173
	v_add_f32_e32 v174, 1.0, v174
	v_rcp_f32_e32 v171, v171
	v_rcp_f32_e32 v172, v172
	v_rcp_f32_e32 v173, v173
	v_rcp_f32_e32 v174, v174
	s_nop 0
	v_mul_f32_e32 v171, v38, v171
	v_mul_f32_e32 v172, v39, v172
	v_mul_f32_e32 v173, v40, v173
	v_mul_f32_e32 v174, v41, v174
	v_mul_f32_e32 v171, v54, v171
	v_mul_f32_e32 v172, v55, v172
	v_mul_f32_e32 v173, v56, v173
	v_mul_f32_e32 v174, v57, v174
	v_cvt_pk_bf16_f32 v179, v171, v171
	v_cvt_pk_bf16_f32 v180, v172, v172
	v_cvt_pk_bf16_f32 v181, v173, v173
	v_cvt_pk_bf16_f32 v182, v174, v174
	global_store_short v162, v179, s[66:67]
	global_store_short v163, v180, s[66:67]
	global_store_short v164, v181, s[66:67]
	global_store_short v165, v182, s[66:67]
	s_add_u32 s66, s66, 0xb000
	s_addc_u32 s67, s67, 0
	v_mul_f32_e32 v171, 0xbfb8aa3b, v42
	v_mul_f32_e32 v172, 0xbfb8aa3b, v43
	v_mul_f32_e32 v173, 0xbfb8aa3b, v44
	v_mul_f32_e32 v174, 0xbfb8aa3b, v45
	v_exp_f32_e32 v171, v171
	v_exp_f32_e32 v172, v172
	v_exp_f32_e32 v173, v173
	v_exp_f32_e32 v174, v174
	s_nop 0
	v_add_f32_e32 v171, 1.0, v171
	v_add_f32_e32 v172, 1.0, v172
	v_add_f32_e32 v173, 1.0, v173
	v_add_f32_e32 v174, 1.0, v174
	v_rcp_f32_e32 v171, v171
	v_rcp_f32_e32 v172, v172
	v_rcp_f32_e32 v173, v173
	v_rcp_f32_e32 v174, v174
	s_nop 0
	v_mul_f32_e32 v171, v42, v171
	v_mul_f32_e32 v172, v43, v172
	v_mul_f32_e32 v173, v44, v173
	v_mul_f32_e32 v174, v45, v174
	v_mul_f32_e32 v171, v58, v171
	v_mul_f32_e32 v172, v59, v172
	v_mul_f32_e32 v173, v60, v173
	v_mul_f32_e32 v174, v61, v174
	v_cvt_pk_bf16_f32 v179, v171, v171
	v_cvt_pk_bf16_f32 v180, v172, v172
	v_cvt_pk_bf16_f32 v181, v173, v173
	v_cvt_pk_bf16_f32 v182, v174, v174
	global_store_short v162, v179, s[66:67]
	global_store_short v163, v180, s[66:67]
	global_store_short v164, v181, s[66:67]
	global_store_short v165, v182, s[66:67]
	s_add_u32 s66, s66, 0xb000
	s_addc_u32 s67, s67, 0
	v_mul_f32_e32 v171, 0xbfb8aa3b, v46
	v_mul_f32_e32 v172, 0xbfb8aa3b, v47
	v_mul_f32_e32 v173, 0xbfb8aa3b, v48
	v_mul_f32_e32 v174, 0xbfb8aa3b, v49
	v_exp_f32_e32 v171, v171
	v_exp_f32_e32 v172, v172
	v_exp_f32_e32 v173, v173
	v_exp_f32_e32 v174, v174
	s_nop 0
	v_add_f32_e32 v171, 1.0, v171
	v_add_f32_e32 v172, 1.0, v172
	v_add_f32_e32 v173, 1.0, v173
	v_add_f32_e32 v174, 1.0, v174
	v_rcp_f32_e32 v171, v171
	v_rcp_f32_e32 v172, v172
	v_rcp_f32_e32 v173, v173
	v_rcp_f32_e32 v174, v174
	s_nop 0
	v_mul_f32_e32 v171, v46, v171
	v_mul_f32_e32 v172, v47, v172
	v_mul_f32_e32 v173, v48, v173
	v_mul_f32_e32 v174, v49, v174
	v_mul_f32_e32 v171, v62, v171
	v_mul_f32_e32 v172, v63, v172
	v_mul_f32_e32 v173, v64, v173
	v_mul_f32_e32 v174, v65, v174
	v_cvt_pk_bf16_f32 v179, v171, v171
	v_cvt_pk_bf16_f32 v180, v172, v172
	v_cvt_pk_bf16_f32 v181, v173, v173
	v_cvt_pk_bf16_f32 v182, v174, v174
	global_store_short v162, v179, s[66:67]
	global_store_short v163, v180, s[66:67]
	global_store_short v164, v181, s[66:67]
	global_store_short v165, v182, s[66:67]
	v_readlane_b32 s62, v246, 14
	s_nop 0
	s_add_i32 s2, s2, s62
	s_branch .Lhw_ffnup_sloop
